# opt11
# speedup vs baseline: 1.0161x; 1.0161x over previous
.LBB0_265:
	ds_read_b128 v[144:147], v134
	ds_read_b128 v[148:151], v134 offset:1024
	ds_read_b128 v[152:155], v134 offset:2048
	ds_read_b128 v[156:159], v134 offset:3072
	s_mov_b32 m0, s82
	s_add_i32 s86, s85, 0xfffdff00
	ds_read_b128 v[160:163], v129
	ds_read_b128 v[164:167], v129 offset:1024
	ds_read_b128 v[168:171], v130
	ds_read_b128 v[172:175], v130 offset:1024
	ds_read_b128 v[176:179], v131
	ds_read_b128 v[180:183], v131 offset:1024
	ds_read_b128 v[184:187], v132
	ds_read_b128 v[188:191], v132 offset:1024
	buffer_load_dwordx4 v133, s[56:59], s86 offen lds
	s_add_i32 s86, s85, 0xffffff00
	s_mov_b32 m0, s83
	s_nop 0
	buffer_load_dwordx4 v133, s[56:59], s86 offen lds
	s_waitcnt lgkmcnt(8)
	s_barrier
	s_waitcnt lgkmcnt(0)
	s_setprio 1
	s_waitcnt lgkmcnt(7)
	v_mfma_f32_16x16x32_bf16 v[28:31], v[160:163], v[144:147], v[28:31]
	v_mfma_f32_16x16x32_bf16 v[24:27], v[160:163], v[152:155], v[24:27]
	s_waitcnt lgkmcnt(5)
	v_mfma_f32_16x16x32_bf16 v[20:23], v[168:171], v[144:147], v[20:23]
	v_mfma_f32_16x16x32_bf16 v[16:19], v[168:171], v[152:155], v[16:19]
	s_waitcnt lgkmcnt(3)
	v_mfma_f32_16x16x32_bf16 v[12:15], v[176:179], v[144:147], v[12:15]
	v_mfma_f32_16x16x32_bf16 v[8:11], v[176:179], v[152:155], v[8:11]
	s_waitcnt lgkmcnt(1)
	v_mfma_f32_16x16x32_bf16 v[4:7], v[184:187], v[144:147], v[4:7]
	v_mfma_f32_16x16x32_bf16 v[0:3], v[184:187], v[152:155], v[0:3]
	v_mfma_f32_16x16x32_bf16 v[28:31], v[164:167], v[148:151], v[28:31]
	v_mfma_f32_16x16x32_bf16 v[24:27], v[164:167], v[156:159], v[24:27]
	v_mfma_f32_16x16x32_bf16 v[20:23], v[172:175], v[148:151], v[20:23]
	v_mfma_f32_16x16x32_bf16 v[16:19], v[172:175], v[156:159], v[16:19]
	v_mfma_f32_16x16x32_bf16 v[12:15], v[180:183], v[148:151], v[12:15]
	v_mfma_f32_16x16x32_bf16 v[8:11], v[180:183], v[156:159], v[8:11]
	s_waitcnt lgkmcnt(0)
	v_mfma_f32_16x16x32_bf16 v[4:7], v[188:191], v[148:151], v[4:7]
	v_mfma_f32_16x16x32_bf16 v[0:3], v[188:191], v[156:159], v[0:3]
	s_setprio 0
	s_barrier
	s_mov_b32 m0, s17
	s_add_i32 s86, s85, 0xfff9ff80
	ds_read_b128 v[192:195], v135
	ds_read_b128 v[196:199], v135 offset:1024
	ds_read_b128 v[200:203], v135 offset:2048
	ds_read_b128 v[204:207], v135 offset:3072
	buffer_load_dwordx4 v133, s[4:7], s86 offen lds
	s_add_i32 s87, s85, 0xfffbff80
	s_mov_b32 m0, s40
	s_nop 0
	buffer_load_dwordx4 v133, s[4:7], s87 offen lds
	s_barrier
	s_waitcnt lgkmcnt(0)
	s_setprio 1
	s_waitcnt lgkmcnt(3)
	v_mfma_f32_16x16x32_bf16 v[60:63], v[160:163], v[192:195], v[60:63]
	s_waitcnt lgkmcnt(1)
	v_mfma_f32_16x16x32_bf16 v[56:59], v[160:163], v[200:203], v[56:59]
	v_mfma_f32_16x16x32_bf16 v[52:55], v[168:171], v[192:195], v[52:55]
	v_mfma_f32_16x16x32_bf16 v[48:51], v[168:171], v[200:203], v[48:51]
	v_mfma_f32_16x16x32_bf16 v[44:47], v[176:179], v[192:195], v[44:47]
	v_mfma_f32_16x16x32_bf16 v[40:43], v[176:179], v[200:203], v[40:43]
	v_mfma_f32_16x16x32_bf16 v[36:39], v[184:187], v[192:195], v[36:39]
	v_mfma_f32_16x16x32_bf16 v[32:35], v[184:187], v[200:203], v[32:35]
	v_mfma_f32_16x16x32_bf16 v[60:63], v[164:167], v[196:199], v[60:63]
	s_waitcnt lgkmcnt(0)
	v_mfma_f32_16x16x32_bf16 v[56:59], v[164:167], v[204:207], v[56:59]
	v_mfma_f32_16x16x32_bf16 v[52:55], v[172:175], v[196:199], v[52:55]
	v_mfma_f32_16x16x32_bf16 v[48:51], v[172:175], v[204:207], v[48:51]
	v_mfma_f32_16x16x32_bf16 v[44:47], v[180:183], v[196:199], v[44:47]
	v_mfma_f32_16x16x32_bf16 v[40:43], v[180:183], v[204:207], v[40:43]
	v_mfma_f32_16x16x32_bf16 v[36:39], v[188:191], v[196:199], v[36:39]
	v_mfma_f32_16x16x32_bf16 v[32:35], v[188:191], v[204:207], v[32:35]
	s_setprio 0
	s_mov_b32 m0, s16
	s_barrier
	ds_read_b128 v[160:163], v129 offset:16384
	ds_read_b128 v[164:167], v129 offset:17408
	ds_read_b128 v[168:171], v130 offset:16384
	ds_read_b128 v[172:175], v130 offset:17408
	ds_read_b128 v[176:179], v131 offset:16384
	ds_read_b128 v[180:183], v131 offset:17408
	ds_read_b128 v[184:187], v132 offset:16384
	ds_read_b128 v[188:191], v132 offset:17408
	buffer_load_dwordx4 v133, s[56:59], s86 offen lds
	s_mov_b32 m0, s41
	s_nop 0
	buffer_load_dwordx4 v133, s[56:59], s87 offen lds
	s_barrier
	s_waitcnt lgkmcnt(0)
	s_setprio 1
	s_waitcnt lgkmcnt(7)
	v_mfma_f32_16x16x32_bf16 v[92:95], v[160:163], v[144:147], v[92:95]
	v_mfma_f32_16x16x32_bf16 v[88:91], v[160:163], v[152:155], v[88:91]
	s_waitcnt lgkmcnt(5)
	v_mfma_f32_16x16x32_bf16 v[84:87], v[168:171], v[144:147], v[84:87]
	v_mfma_f32_16x16x32_bf16 v[80:83], v[168:171], v[152:155], v[80:83]
	s_waitcnt lgkmcnt(3)
	v_mfma_f32_16x16x32_bf16 v[76:79], v[176:179], v[144:147], v[76:79]
	v_mfma_f32_16x16x32_bf16 v[72:75], v[176:179], v[152:155], v[72:75]
	s_waitcnt lgkmcnt(1)
	v_mfma_f32_16x16x32_bf16 v[68:71], v[184:187], v[144:147], v[68:71]
	v_mfma_f32_16x16x32_bf16 v[64:67], v[184:187], v[152:155], v[64:67]
	v_mfma_f32_16x16x32_bf16 v[92:95], v[164:167], v[148:151], v[92:95]
	v_mfma_f32_16x16x32_bf16 v[88:91], v[164:167], v[156:159], v[88:91]
	v_mfma_f32_16x16x32_bf16 v[84:87], v[172:175], v[148:151], v[84:87]
	v_mfma_f32_16x16x32_bf16 v[80:83], v[172:175], v[156:159], v[80:83]
	v_mfma_f32_16x16x32_bf16 v[76:79], v[180:183], v[148:151], v[76:79]
	v_mfma_f32_16x16x32_bf16 v[72:75], v[180:183], v[156:159], v[72:75]
	s_waitcnt lgkmcnt(0)
	v_mfma_f32_16x16x32_bf16 v[68:71], v[188:191], v[148:151], v[68:71]
	v_mfma_f32_16x16x32_bf16 v[64:67], v[188:191], v[156:159], v[64:67]
	s_setprio 0
	s_barrier
	s_mov_b32 m0, s42
	s_add_i32 s86, s85, 0xfffdff80
	buffer_load_dwordx4 v133, s[4:7], s86 offen lds
	s_add_i32 s87, s85, 0xffffff80
	s_mov_b32 m0, s43
	s_nop 0
	buffer_load_dwordx4 v133, s[4:7], s87 offen lds
	s_waitcnt vmcnt(6)
	s_barrier
	s_setprio 1
	v_mfma_f32_16x16x32_bf16 v[124:127], v[160:163], v[192:195], v[124:127]
	v_mfma_f32_16x16x32_bf16 v[120:123], v[160:163], v[200:203], v[120:123]
	v_mfma_f32_16x16x32_bf16 v[116:119], v[168:171], v[192:195], v[116:119]
	v_mfma_f32_16x16x32_bf16 v[112:115], v[168:171], v[200:203], v[112:115]
	v_mfma_f32_16x16x32_bf16 v[108:111], v[176:179], v[192:195], v[108:111]
	v_mfma_f32_16x16x32_bf16 v[104:107], v[176:179], v[200:203], v[104:107]
	v_mfma_f32_16x16x32_bf16 v[100:103], v[184:187], v[192:195], v[100:103]
	v_mfma_f32_16x16x32_bf16 v[96:99], v[184:187], v[200:203], v[96:99]
	v_mfma_f32_16x16x32_bf16 v[124:127], v[164:167], v[196:199], v[124:127]
	v_mfma_f32_16x16x32_bf16 v[120:123], v[164:167], v[204:207], v[120:123]
	v_mfma_f32_16x16x32_bf16 v[116:119], v[172:175], v[196:199], v[116:119]
	v_mfma_f32_16x16x32_bf16 v[112:115], v[172:175], v[204:207], v[112:115]
	v_mfma_f32_16x16x32_bf16 v[108:111], v[180:183], v[196:199], v[108:111]
	v_mfma_f32_16x16x32_bf16 v[104:107], v[180:183], v[204:207], v[104:107]
	v_mfma_f32_16x16x32_bf16 v[100:103], v[188:191], v[196:199], v[100:103]
	v_mfma_f32_16x16x32_bf16 v[96:99], v[188:191], v[204:207], v[96:99]
	s_setprio 0
	s_barrier
	ds_read_b128 v[144:147], v136
	ds_read_b128 v[148:151], v136 offset:1024
	ds_read_b128 v[152:155], v136 offset:2048
	ds_read_b128 v[156:159], v136 offset:3072
	s_mov_b32 m0, s45
	ds_read_b128 v[160:163], v129 offset:32768
	ds_read_b128 v[164:167], v129 offset:33792
	ds_read_b128 v[168:171], v130 offset:32768
	ds_read_b128 v[172:175], v130 offset:33792
	ds_read_b128 v[176:179], v131 offset:32768
	ds_read_b128 v[180:183], v131 offset:33792
	ds_read_b128 v[184:187], v132 offset:32768
	ds_read_b128 v[188:191], v132 offset:33792
	buffer_load_dwordx4 v133, s[56:59], s86 offen lds
	s_mov_b32 m0, s46
	s_nop 0
	buffer_load_dwordx4 v133, s[56:59], s87 offen lds
	s_waitcnt lgkmcnt(8)
	s_barrier
	s_waitcnt lgkmcnt(0)
	s_setprio 1
	s_waitcnt lgkmcnt(7)
	v_mfma_f32_16x16x32_bf16 v[28:31], v[160:163], v[144:147], v[28:31]
	v_mfma_f32_16x16x32_bf16 v[24:27], v[160:163], v[152:155], v[24:27]
	s_waitcnt lgkmcnt(5)
	v_mfma_f32_16x16x32_bf16 v[20:23], v[168:171], v[144:147], v[20:23]
	v_mfma_f32_16x16x32_bf16 v[16:19], v[168:171], v[152:155], v[16:19]
	s_waitcnt lgkmcnt(3)
	v_mfma_f32_16x16x32_bf16 v[12:15], v[176:179], v[144:147], v[12:15]
	v_mfma_f32_16x16x32_bf16 v[8:11], v[176:179], v[152:155], v[8:11]
	s_waitcnt lgkmcnt(1)
	v_mfma_f32_16x16x32_bf16 v[4:7], v[184:187], v[144:147], v[4:7]
	v_mfma_f32_16x16x32_bf16 v[0:3], v[184:187], v[152:155], v[0:3]
	v_mfma_f32_16x16x32_bf16 v[28:31], v[164:167], v[148:151], v[28:31]
	v_mfma_f32_16x16x32_bf16 v[24:27], v[164:167], v[156:159], v[24:27]
	v_mfma_f32_16x16x32_bf16 v[20:23], v[172:175], v[148:151], v[20:23]
	v_mfma_f32_16x16x32_bf16 v[16:19], v[172:175], v[156:159], v[16:19]
	v_mfma_f32_16x16x32_bf16 v[12:15], v[180:183], v[148:151], v[12:15]
	v_mfma_f32_16x16x32_bf16 v[8:11], v[180:183], v[156:159], v[8:11]
	s_waitcnt lgkmcnt(0)
	v_mfma_f32_16x16x32_bf16 v[4:7], v[188:191], v[148:151], v[4:7]
	v_mfma_f32_16x16x32_bf16 v[0:3], v[188:191], v[156:159], v[0:3]
	s_setprio 0
	s_barrier
	s_mov_b32 m0, s14
	s_add_i32 s86, s85, 0xfffa0000
	ds_read_b128 v[192:195], v137
	ds_read_b128 v[196:199], v137 offset:1024
	ds_read_b128 v[200:203], v137 offset:2048
	ds_read_b128 v[204:207], v137 offset:3072
	buffer_load_dwordx4 v133, s[4:7], s86 offen lds
	s_add_i32 s87, s85, 0xfffc0000
	s_mov_b32 m0, s15
	s_nop 0
	buffer_load_dwordx4 v133, s[4:7], s87 offen lds
	s_barrier
	s_waitcnt lgkmcnt(0)
	s_setprio 1
	s_waitcnt lgkmcnt(3)
	v_mfma_f32_16x16x32_bf16 v[60:63], v[160:163], v[192:195], v[60:63]
	s_waitcnt lgkmcnt(1)
	v_mfma_f32_16x16x32_bf16 v[56:59], v[160:163], v[200:203], v[56:59]
	v_mfma_f32_16x16x32_bf16 v[52:55], v[168:171], v[192:195], v[52:55]
	v_mfma_f32_16x16x32_bf16 v[48:51], v[168:171], v[200:203], v[48:51]
	v_mfma_f32_16x16x32_bf16 v[44:47], v[176:179], v[192:195], v[44:47]
	v_mfma_f32_16x16x32_bf16 v[40:43], v[176:179], v[200:203], v[40:43]
	v_mfma_f32_16x16x32_bf16 v[36:39], v[184:187], v[192:195], v[36:39]
	v_mfma_f32_16x16x32_bf16 v[32:35], v[184:187], v[200:203], v[32:35]
	v_mfma_f32_16x16x32_bf16 v[60:63], v[164:167], v[196:199], v[60:63]
	s_waitcnt lgkmcnt(0)
	v_mfma_f32_16x16x32_bf16 v[56:59], v[164:167], v[204:207], v[56:59]
	v_mfma_f32_16x16x32_bf16 v[52:55], v[172:175], v[196:199], v[52:55]
	v_mfma_f32_16x16x32_bf16 v[48:51], v[172:175], v[204:207], v[48:51]
	v_mfma_f32_16x16x32_bf16 v[44:47], v[180:183], v[196:199], v[44:47]
	v_mfma_f32_16x16x32_bf16 v[40:43], v[180:183], v[204:207], v[40:43]
	v_mfma_f32_16x16x32_bf16 v[36:39], v[188:191], v[196:199], v[36:39]
	v_mfma_f32_16x16x32_bf16 v[32:35], v[188:191], v[204:207], v[32:35]
	s_setprio 0
	s_mov_b32 m0, s47
	s_barrier
	ds_read_b128 v[160:163], v129 offset:49152
	ds_read_b128 v[164:167], v129 offset:50176
	ds_read_b128 v[168:171], v130 offset:49152
	ds_read_b128 v[172:175], v130 offset:50176
	ds_read_b128 v[176:179], v131 offset:49152
	ds_read_b128 v[180:183], v131 offset:50176
	ds_read_b128 v[184:187], v132 offset:49152
	ds_read_b128 v[188:191], v132 offset:50176
	buffer_load_dwordx4 v133, s[56:59], s86 offen lds
	s_mov_b32 m0, s67
	s_nop 0
	buffer_load_dwordx4 v133, s[56:59], s87 offen lds
	s_barrier
; #define LDA(dst, b, h)                                                                             \
;   _Pragma("unroll") for (int m = 0; m < 4; ++m) _Pragma("unroll") for (int k = 0; k < 2; ++k)      \
;       dst[m][k] = *reinterpret_cast<const bf16x8*>(SA(b, h) + lds_byte(wr * 64 + m * 16 + fr, k * 32 + fq * 8))
; #define LDB(dst, b, h)                                                                             \
;   _Pragma("unroll") for (int n = 0; n < 2; ++n) _Pragma("unroll") for (int k = 0; k < 2; ++k)      \
;       dst[n][k] = *reinterpret_cast<const bf16x8*>(SB(b, h) + lds_byte(wc * 32 + n * 16 + fr, k * 32 + fq * 8))
; #define WAIT_V(n) asm volatile("s_waitcnt vmcnt(" #n ")" ::: "memory")
; #define WAIT_L(n) asm volatile("s_waitcnt lgkmcnt(" #n ")" ::: "memory")
; #define BAR __builtin_amdgcn_s_barrier()
; template <bool PEEL = false>
; __device__ __forceinline__ void gemm_tile(f32x4 (&acc)[2][2][4][2], const u16* __restrict__ A, int lda,
;                                           const u16* __restrict__ B, int K) {
;     ...
;     for (int t = 2; t < nt - 2; t += 2) { KLOOP_BODY(t) }
;   } else {
;     for (int t = 0; t < nt - 2; t += 2) { KLOOP_BODY(t) }
;   }
;   {
;     LDB(B0, 0, 0); LDA(At, 0, 0); STAGE_A(SA(1, 1), 1, nt - 1);
;     BAR; WAIT_L(0); MMA(0, 0, At, B0); BAR;
;     LDB(B1, 0, 1); BAR; WAIT_L(0); MMA(0, 1, At, B1); BAR;
;     LDA(At, 0, 1); WAIT_V(4); BAR; WAIT_L(0); MMA(1, 0, At, B0); MMA(1, 1, At, B1); BAR;
	s_waitcnt lgkmcnt(0)
	s_setprio 1
	s_waitcnt lgkmcnt(7)
	v_mfma_f32_16x16x32_bf16 v[92:95], v[160:163], v[144:147], v[92:95]
	v_mfma_f32_16x16x32_bf16 v[88:91], v[160:163], v[152:155], v[88:91]
	s_waitcnt lgkmcnt(5)
	v_mfma_f32_16x16x32_bf16 v[84:87], v[168:171], v[144:147], v[84:87]
	v_mfma_f32_16x16x32_bf16 v[80:83], v[168:171], v[152:155], v[80:83]
	s_waitcnt lgkmcnt(3)
	v_mfma_f32_16x16x32_bf16 v[76:79], v[176:179], v[144:147], v[76:79]
	v_mfma_f32_16x16x32_bf16 v[72:75], v[176:179], v[152:155], v[72:75]
	s_waitcnt lgkmcnt(1)
	v_mfma_f32_16x16x32_bf16 v[68:71], v[184:187], v[144:147], v[68:71]
	v_mfma_f32_16x16x32_bf16 v[64:67], v[184:187], v[152:155], v[64:67]
	v_mfma_f32_16x16x32_bf16 v[92:95], v[164:167], v[148:151], v[92:95]
	v_mfma_f32_16x16x32_bf16 v[88:91], v[164:167], v[156:159], v[88:91]
	v_mfma_f32_16x16x32_bf16 v[84:87], v[172:175], v[148:151], v[84:87]
	v_mfma_f32_16x16x32_bf16 v[80:83], v[172:175], v[156:159], v[80:83]
	v_mfma_f32_16x16x32_bf16 v[76:79], v[180:183], v[148:151], v[76:79]
	v_mfma_f32_16x16x32_bf16 v[72:75], v[180:183], v[156:159], v[72:75]
	s_waitcnt lgkmcnt(0)
	v_mfma_f32_16x16x32_bf16 v[68:71], v[188:191], v[148:151], v[68:71]
	v_mfma_f32_16x16x32_bf16 v[64:67], v[188:191], v[156:159], v[64:67]
	s_setprio 0
	s_barrier
	s_add_i32 s86, s85, 0xfffe0000
	s_mov_b32 m0, s78
	s_nop 0
	buffer_load_dwordx4 v133, s[4:7], s86 offen lds
	s_mov_b32 m0, s79
	s_nop 0
	buffer_load_dwordx4 v133, s[4:7], s85 offen lds
	s_waitcnt vmcnt(6)
	s_barrier
	s_setprio 1
	v_mfma_f32_16x16x32_bf16 v[124:127], v[160:163], v[192:195], v[124:127]
	v_mfma_f32_16x16x32_bf16 v[120:123], v[160:163], v[200:203], v[120:123]
	v_mfma_f32_16x16x32_bf16 v[116:119], v[168:171], v[192:195], v[116:119]
	v_mfma_f32_16x16x32_bf16 v[112:115], v[168:171], v[200:203], v[112:115]
	v_mfma_f32_16x16x32_bf16 v[108:111], v[176:179], v[192:195], v[108:111]
	v_mfma_f32_16x16x32_bf16 v[104:107], v[176:179], v[200:203], v[104:107]
	v_mfma_f32_16x16x32_bf16 v[100:103], v[184:187], v[192:195], v[100:103]
	v_mfma_f32_16x16x32_bf16 v[96:99], v[184:187], v[200:203], v[96:99]
	v_mfma_f32_16x16x32_bf16 v[124:127], v[164:167], v[196:199], v[124:127]
	v_mfma_f32_16x16x32_bf16 v[120:123], v[164:167], v[204:207], v[120:123]
	v_mfma_f32_16x16x32_bf16 v[116:119], v[172:175], v[196:199], v[116:119]
	v_mfma_f32_16x16x32_bf16 v[112:115], v[172:175], v[204:207], v[112:115]
	v_mfma_f32_16x16x32_bf16 v[108:111], v[180:183], v[196:199], v[108:111]
	v_mfma_f32_16x16x32_bf16 v[104:107], v[180:183], v[204:207], v[104:107]
	v_mfma_f32_16x16x32_bf16 v[100:103], v[188:191], v[196:199], v[100:103]
	v_mfma_f32_16x16x32_bf16 v[96:99], v[188:191], v[204:207], v[96:99]
	s_setprio 0
	s_add_i32 s84, s84, 2
	s_addk_i32 s85, 0x100
	s_cmp_lt_u32 s84, 12
	s_barrier
	s_cbranch_scc1 .LBB0_265
	v_mov_b32_e32 v244, v133
	s_mov_b32 m0, s82
	ds_read_b128 v[144:147], v134
	ds_read_b128 v[148:151], v134 offset:1024
	ds_read_b128 v[152:155], v134 offset:2048
	ds_read_b128 v[156:159], v134 offset:3072
	ds_read_b128 v[160:163], v129
	ds_read_b128 v[164:167], v129 offset:1024
	ds_read_b128 v[168:171], v130
	ds_read_b128 v[172:175], v130 offset:1024
	ds_read_b128 v[176:179], v131
	ds_read_b128 v[180:183], v131 offset:1024
	ds_read_b128 v[184:187], v132
	ds_read_b128 v[188:191], v132 offset:1024
	buffer_load_dwordx4 v133, s[56:59], s38 offen lds
	s_mov_b32 m0, s83
	s_nop 0
	buffer_load_dwordx4 v133, s[56:59], s39 offen lds
	s_barrier
	s_waitcnt lgkmcnt(0)
	s_setprio 1
	s_waitcnt lgkmcnt(7)
	v_mfma_f32_16x16x32_bf16 v[28:31], v[160:163], v[144:147], v[28:31]
	v_mfma_f32_16x16x32_bf16 v[24:27], v[160:163], v[152:155], v[24:27]
	s_waitcnt lgkmcnt(5)
	v_mfma_f32_16x16x32_bf16 v[20:23], v[168:171], v[144:147], v[20:23]
	v_mfma_f32_16x16x32_bf16 v[16:19], v[168:171], v[152:155], v[16:19]
	s_waitcnt lgkmcnt(3)
	v_mfma_f32_16x16x32_bf16 v[12:15], v[176:179], v[144:147], v[12:15]
	v_mfma_f32_16x16x32_bf16 v[8:11], v[176:179], v[152:155], v[8:11]
	s_waitcnt lgkmcnt(1)
	v_mfma_f32_16x16x32_bf16 v[4:7], v[184:187], v[144:147], v[4:7]
	v_mfma_f32_16x16x32_bf16 v[0:3], v[184:187], v[152:155], v[0:3]
	v_mfma_f32_16x16x32_bf16 v[28:31], v[164:167], v[148:151], v[28:31]
	v_mfma_f32_16x16x32_bf16 v[24:27], v[164:167], v[156:159], v[24:27]
	v_mfma_f32_16x16x32_bf16 v[20:23], v[172:175], v[148:151], v[20:23]
	v_mfma_f32_16x16x32_bf16 v[16:19], v[172:175], v[156:159], v[16:19]
	v_mfma_f32_16x16x32_bf16 v[12:15], v[180:183], v[148:151], v[12:15]
	v_mfma_f32_16x16x32_bf16 v[8:11], v[180:183], v[156:159], v[8:11]
	s_waitcnt lgkmcnt(0)
	v_mfma_f32_16x16x32_bf16 v[4:7], v[188:191], v[148:151], v[4:7]
	v_mfma_f32_16x16x32_bf16 v[0:3], v[188:191], v[156:159], v[0:3]
	s_setprio 0
	s_barrier
	ds_read_b128 v[192:195], v135
	ds_read_b128 v[196:199], v135 offset:1024
	ds_read_b128 v[200:203], v135 offset:2048
	ds_read_b128 v[204:207], v135 offset:3072
	s_barrier
	s_waitcnt lgkmcnt(0)
	s_setprio 1
	s_waitcnt lgkmcnt(3)
	v_mfma_f32_16x16x32_bf16 v[60:63], v[160:163], v[192:195], v[60:63]
	s_waitcnt lgkmcnt(1)
	v_mfma_f32_16x16x32_bf16 v[56:59], v[160:163], v[200:203], v[56:59]
	v_mfma_f32_16x16x32_bf16 v[52:55], v[168:171], v[192:195], v[52:55]
	v_mfma_f32_16x16x32_bf16 v[48:51], v[168:171], v[200:203], v[48:51]
	v_mfma_f32_16x16x32_bf16 v[44:47], v[176:179], v[192:195], v[44:47]
	v_mfma_f32_16x16x32_bf16 v[40:43], v[176:179], v[200:203], v[40:43]
	v_mfma_f32_16x16x32_bf16 v[36:39], v[184:187], v[192:195], v[36:39]
	v_mfma_f32_16x16x32_bf16 v[32:35], v[184:187], v[200:203], v[32:35]
	v_mfma_f32_16x16x32_bf16 v[60:63], v[164:167], v[196:199], v[60:63]
	s_waitcnt lgkmcnt(0)
	v_mfma_f32_16x16x32_bf16 v[56:59], v[164:167], v[204:207], v[56:59]
	v_mfma_f32_16x16x32_bf16 v[52:55], v[172:175], v[196:199], v[52:55]
	v_mfma_f32_16x16x32_bf16 v[48:51], v[172:175], v[204:207], v[48:51]
	v_mfma_f32_16x16x32_bf16 v[44:47], v[180:183], v[196:199], v[44:47]
	v_mfma_f32_16x16x32_bf16 v[40:43], v[180:183], v[204:207], v[40:43]
	v_mfma_f32_16x16x32_bf16 v[36:39], v[188:191], v[196:199], v[36:39]
	v_mfma_f32_16x16x32_bf16 v[32:35], v[188:191], v[204:207], v[32:35]
	s_setprio 0
	s_barrier
	ds_read_b128 v[160:163], v129 offset:16384
	ds_read_b128 v[164:167], v129 offset:17408
	ds_read_b128 v[168:171], v130 offset:16384
	ds_read_b128 v[172:175], v130 offset:17408
	ds_read_b128 v[176:179], v131 offset:16384
	ds_read_b128 v[180:183], v131 offset:17408
	ds_read_b128 v[184:187], v132 offset:16384
	ds_read_b128 v[188:191], v132 offset:17408
	s_cmp_eq_u32 s21, 15
	s_cbranch_scc1 .Lt3_a_last
	s_add_i32 s14, s21, 1
	s_lshl_b32 s14, s14, 19
	s_add_u32 s4, s1, s14
	s_addc_u32 s5, s20, 0
	s_and_b32 s5, s5, 0xffff
	s_mov_b32 m0, s17
	s_nop 0
	buffer_load_dwordx4 v244, s[4:7], 0 offen lds
	s_mov_b32 m0, s40
	s_nop 0
	buffer_load_dwordx4 v244, s[4:7], s7 offen lds
	s_mov_b32 m0, s16
	s_nop 0
	buffer_load_dwordx4 v244, s[56:59], 0 offen lds
	s_mov_b32 m0, s41
	s_nop 0
	buffer_load_dwordx4 v244, s[56:59], s7 offen lds
	s_waitcnt vmcnt(8)
	s_branch .Lt3_a_join

; #define LDA(dst, b, h)                                                                             \
;   _Pragma("unroll") for (int m = 0; m < 4; ++m) _Pragma("unroll") for (int k = 0; k < 2; ++k)      \
;       dst[m][k] = *reinterpret_cast<const bf16x8*>(SA(b, h) + lds_byte(wr * 64 + m * 16 + fr, k * 32 + fq * 8))
; #define LDB(dst, b, h)                                                                             \
;   _Pragma("unroll") for (int n = 0; n < 2; ++n) _Pragma("unroll") for (int k = 0; k < 2; ++k)      \
;       dst[n][k] = *reinterpret_cast<const bf16x8*>(SB(b, h) + lds_byte(wc * 32 + n * 16 + fr, k * 32 + fq * 8))
; #define WAIT_V(n) asm volatile("s_waitcnt vmcnt(" #n ")" ::: "memory")
; #define WAIT_L(n) asm volatile("s_waitcnt lgkmcnt(" #n ")" ::: "memory")
; #define BAR __builtin_amdgcn_s_barrier()
; template <bool PEEL = false>
; __device__ __forceinline__ void gemm_tile(f32x4 (&acc)[2][2][4][2], const u16* __restrict__ A, int lda,
;                                           const u16* __restrict__ B, int K) {
;     ...
;     LDA(At, 0, 1); WAIT_V(4); BAR; WAIT_L(0); MMA(1, 0, At, B0); MMA(1, 1, At, B1); BAR;
;   }
;   {
;     LDB(B0, 1, 0); LDA(At, 1, 0); WAIT_V(2); BAR; WAIT_L(0); MMA(0, 0, At, B0); BAR;
;     LDB(B1, 1, 1); WAIT_V(0); BAR; WAIT_L(0); MMA(0, 1, At, B1); BAR;
.Lt3_a_join:
	s_barrier
	s_waitcnt lgkmcnt(0)
	s_setprio 1
	s_waitcnt lgkmcnt(7)
	v_mfma_f32_16x16x32_bf16 v[92:95], v[160:163], v[144:147], v[92:95]
	v_mfma_f32_16x16x32_bf16 v[88:91], v[160:163], v[152:155], v[88:91]
	s_waitcnt lgkmcnt(5)
	v_mfma_f32_16x16x32_bf16 v[84:87], v[168:171], v[144:147], v[84:87]
	v_mfma_f32_16x16x32_bf16 v[80:83], v[168:171], v[152:155], v[80:83]
	s_waitcnt lgkmcnt(3)
	v_mfma_f32_16x16x32_bf16 v[76:79], v[176:179], v[144:147], v[76:79]
	v_mfma_f32_16x16x32_bf16 v[72:75], v[176:179], v[152:155], v[72:75]
	s_waitcnt lgkmcnt(1)
	v_mfma_f32_16x16x32_bf16 v[68:71], v[184:187], v[144:147], v[68:71]
	v_mfma_f32_16x16x32_bf16 v[64:67], v[184:187], v[152:155], v[64:67]
	v_mfma_f32_16x16x32_bf16 v[208:211], v[164:167], v[148:151], v[92:95]
	v_mfma_f32_16x16x32_bf16 v[212:215], v[164:167], v[156:159], v[88:91]
	v_mfma_f32_16x16x32_bf16 v[216:219], v[172:175], v[148:151], v[84:87]
	v_mfma_f32_16x16x32_bf16 v[220:223], v[172:175], v[156:159], v[80:83]
	v_mfma_f32_16x16x32_bf16 v[224:227], v[180:183], v[148:151], v[76:79]
	v_mfma_f32_16x16x32_bf16 v[228:231], v[180:183], v[156:159], v[72:75]
	s_waitcnt lgkmcnt(0)
	v_mfma_f32_16x16x32_bf16 v[144:147], v[188:191], v[148:151], v[68:71]
	v_mfma_f32_16x16x32_bf16 v[148:151], v[188:191], v[156:159], v[64:67]
	s_setprio 0
	s_setprio 1
	v_mfma_f32_16x16x32_bf16 v[64:67], v[160:163], v[192:195], v[124:127]
	v_mfma_f32_16x16x32_bf16 v[152:155], v[164:167], v[196:199], v[64:67]
	v_mfma_f32_16x16x32_bf16 v[64:67], v[160:163], v[200:203], v[120:123]
	v_mfma_f32_16x16x32_bf16 v[156:159], v[164:167], v[204:207], v[64:67]
	v_mfma_f32_16x16x32_bf16 v[64:67], v[168:171], v[192:195], v[116:119]
	v_mfma_f32_16x16x32_bf16 v[160:163], v[172:175], v[196:199], v[64:67]
	v_mfma_f32_16x16x32_bf16 v[64:67], v[168:171], v[200:203], v[112:115]
	v_mfma_f32_16x16x32_bf16 v[164:167], v[172:175], v[204:207], v[64:67]
	v_mfma_f32_16x16x32_bf16 v[64:67], v[176:179], v[192:195], v[108:111]
	v_mfma_f32_16x16x32_bf16 v[168:171], v[180:183], v[196:199], v[64:67]
	v_mfma_f32_16x16x32_bf16 v[64:67], v[176:179], v[200:203], v[104:107]
	v_mfma_f32_16x16x32_bf16 v[172:175], v[180:183], v[204:207], v[64:67]
	v_mfma_f32_16x16x32_bf16 v[64:67], v[184:187], v[192:195], v[100:103]
	v_mfma_f32_16x16x32_bf16 v[176:179], v[188:191], v[196:199], v[64:67]
	v_mfma_f32_16x16x32_bf16 v[64:67], v[184:187], v[200:203], v[96:99]
	v_mfma_f32_16x16x32_bf16 v[180:183], v[188:191], v[204:207], v[64:67]
	s_setprio 0
	s_barrier
	ds_read_b128 v[184:187], v136
	ds_read_b128 v[188:191], v136 offset:1024
	ds_read_b128 v[192:195], v136 offset:2048
	ds_read_b128 v[196:199], v136 offset:3072
	ds_read_b128 v[72:75], v129 offset:32768
	ds_read_b128 v[76:79], v129 offset:33792
	ds_read_b128 v[88:91], v130 offset:32768
	ds_read_b128 v[92:95], v130 offset:33792
	ds_read_b128 v[200:203], v131 offset:32768
	ds_read_b128 v[204:207], v131 offset:33792
	ds_read_b128 v[232:235], v132 offset:32768
	ds_read_b128 v[236:239], v132 offset:33792
	s_cmp_eq_u32 s21, 15
	s_cbranch_scc1 .Lt3_b_last
	s_mov_b32 m0, s42
	s_nop 0
	buffer_load_dwordx4 v244, s[4:7], s22 offen lds
	s_mov_b32 m0, s43
	s_nop 0
	buffer_load_dwordx4 v244, s[4:7], s23 offen lds
	s_waitcnt vmcnt(8)
	s_branch .Lt3_b_join

; #define LDA(dst, b, h)                                                                             \
;   _Pragma("unroll") for (int m = 0; m < 4; ++m) _Pragma("unroll") for (int k = 0; k < 2; ++k)      \
;       dst[m][k] = *reinterpret_cast<const bf16x8*>(SA(b, h) + lds_byte(wr * 64 + m * 16 + fr, k * 32 + fq * 8))
; #define LDB(dst, b, h)                                                                             \
;   _Pragma("unroll") for (int n = 0; n < 2; ++n) _Pragma("unroll") for (int k = 0; k < 2; ++k)      \
;       dst[n][k] = *reinterpret_cast<const bf16x8*>(SB(b, h) + lds_byte(wc * 32 + n * 16 + fr, k * 32 + fq * 8))
; #define WAIT_V(n) asm volatile("s_waitcnt vmcnt(" #n ")" ::: "memory")
; #define WAIT_L(n) asm volatile("s_waitcnt lgkmcnt(" #n ")" ::: "memory")
; #define BAR __builtin_amdgcn_s_barrier()
; template <bool PEEL = false>
; __device__ __forceinline__ void gemm_tile(f32x4 (&acc)[2][2][4][2], const u16* __restrict__ A, int lda,
;                                           const u16* __restrict__ B, int K) {
;     ...
;     LDB(B0, 1, 0); LDA(At, 1, 0); WAIT_V(2); BAR; WAIT_L(0); MMA(0, 0, At, B0); BAR;
;     LDB(B1, 1, 1); WAIT_V(0); BAR; WAIT_L(0); MMA(0, 1, At, B1); BAR;
.Lt3_b_join:
	s_barrier
	s_waitcnt lgkmcnt(0)
	s_setprio 1
	s_waitcnt lgkmcnt(7)
	v_mfma_f32_16x16x32_bf16 v[28:31], v[72:75], v[184:187], v[28:31]
	v_mfma_f32_16x16x32_bf16 v[24:27], v[72:75], v[192:195], v[24:27]
	s_waitcnt lgkmcnt(5)
	v_mfma_f32_16x16x32_bf16 v[20:23], v[88:91], v[184:187], v[20:23]
	v_mfma_f32_16x16x32_bf16 v[16:19], v[88:91], v[192:195], v[16:19]
	s_waitcnt lgkmcnt(3)
	v_mfma_f32_16x16x32_bf16 v[12:15], v[200:203], v[184:187], v[12:15]
	v_mfma_f32_16x16x32_bf16 v[8:11], v[200:203], v[192:195], v[8:11]
	s_waitcnt lgkmcnt(1)
	v_mfma_f32_16x16x32_bf16 v[4:7], v[232:235], v[184:187], v[4:7]
	v_mfma_f32_16x16x32_bf16 v[0:3], v[232:235], v[192:195], v[0:3]
	v_mfma_f32_16x16x32_bf16 v[112:115], v[76:79], v[188:191], v[28:31]
	v_mfma_f32_16x16x32_bf16 v[116:119], v[76:79], v[196:199], v[24:27]
	v_mfma_f32_16x16x32_bf16 v[96:99], v[92:95], v[188:191], v[20:23]
	v_mfma_f32_16x16x32_bf16 v[100:103], v[92:95], v[196:199], v[16:19]
	v_mfma_f32_16x16x32_bf16 v[80:83], v[204:207], v[188:191], v[12:15]
	v_mfma_f32_16x16x32_bf16 v[84:87], v[204:207], v[196:199], v[8:11]
	s_waitcnt lgkmcnt(0)
	v_mfma_f32_16x16x32_bf16 v[64:67], v[236:239], v[188:191], v[4:7]
	v_mfma_f32_16x16x32_bf16 v[68:71], v[236:239], v[196:199], v[0:3]
	s_setprio 0
	s_barrier
	ds_read_b128 v[8:11], v137
	ds_read_b128 v[12:15], v137 offset:1024
	ds_read_b128 v[240:243], v137 offset:2048
	ds_read_b128 v[134:137], v137 offset:3072
	s_cmp_eq_u32 s21, 15
	s_cbranch_scc1 .Lt3_c_last
	s_mov_b32 m0, s45
	s_nop 0
	buffer_load_dwordx4 v244, s[56:59], s22 offen lds
	s_mov_b32 m0, s46
	s_nop 0
	buffer_load_dwordx4 v244, s[56:59], s23 offen lds
	s_waitcnt vmcnt(8)
	s_branch .Lt3_c_join

; #define LDA(dst, b, h)                                                                             \
;   _Pragma("unroll") for (int m = 0; m < 4; ++m) _Pragma("unroll") for (int k = 0; k < 2; ++k)      \
;       dst[m][k] = *reinterpret_cast<const bf16x8*>(SA(b, h) + lds_byte(wr * 64 + m * 16 + fr, k * 32 + fq * 8))
; #define LDB(dst, b, h)                                                                             \
;   _Pragma("unroll") for (int n = 0; n < 2; ++n) _Pragma("unroll") for (int k = 0; k < 2; ++k)      \
;       dst[n][k] = *reinterpret_cast<const bf16x8*>(SB(b, h) + lds_byte(wc * 32 + n * 16 + fr, k * 32 + fq * 8))
; #define WAIT_V(n) asm volatile("s_waitcnt vmcnt(" #n ")" ::: "memory")
; #define WAIT_L(n) asm volatile("s_waitcnt lgkmcnt(" #n ")" ::: "memory")
; #define BAR __builtin_amdgcn_s_barrier()
; template <bool PEEL = false>
; __device__ __forceinline__ void gemm_tile(f32x4 (&acc)[2][2][4][2], const u16* __restrict__ A, int lda,
;                                           const u16* __restrict__ B, int K) {
;     ...
;   STAGE_B(SB(0, 0), 0, 0); STAGE_A(SA(0, 0), 0, 0);
;   STAGE_B(SB(0, 1), 1, 0); STAGE_A(SA(0, 1), 1, 0);
;   if (wr == 1) BAR;
;   WAIT_V(4); BAR;
;   STAGE_B(SB(1, 0), 0, 1); STAGE_A(SA(1, 0), 0, 1); STAGE_B(SB(1, 1), 1, 1);
;     ...
;     LDB(B1, 1, 1); WAIT_V(0); BAR; WAIT_L(0); MMA(0, 1, At, B1); BAR;
;     LDA(At, 1, 1); BAR; WAIT_L(0); MMA(1, 0, At, B0); MMA(1, 1, At, B1); BAR;
;   }
;   if (wr == 0) BAR;
.Lt3_c_join:
	s_barrier
	s_waitcnt lgkmcnt(0)
	s_setprio 1
	s_waitcnt lgkmcnt(3)
	v_mfma_f32_16x16x32_bf16 v[0:3], v[72:75], v[8:11], v[60:63]
	s_waitcnt lgkmcnt(2)
	v_mfma_f32_16x16x32_bf16 v[120:123], v[76:79], v[12:15], v[0:3]
	s_waitcnt lgkmcnt(1)
	v_mfma_f32_16x16x32_bf16 v[0:3], v[72:75], v[240:243], v[56:59]
	s_waitcnt lgkmcnt(0)
	v_mfma_f32_16x16x32_bf16 v[124:127], v[76:79], v[134:137], v[0:3]
	v_mfma_f32_16x16x32_bf16 v[0:3], v[88:91], v[8:11], v[52:55]
	v_mfma_f32_16x16x32_bf16 v[104:107], v[92:95], v[12:15], v[0:3]
	v_mfma_f32_16x16x32_bf16 v[0:3], v[88:91], v[240:243], v[48:51]
	v_mfma_f32_16x16x32_bf16 v[108:111], v[92:95], v[134:137], v[0:3]
	v_mfma_f32_16x16x32_bf16 v[0:3], v[200:203], v[8:11], v[44:47]
	v_mfma_f32_16x16x32_bf16 v[88:91], v[204:207], v[12:15], v[0:3]
	v_mfma_f32_16x16x32_bf16 v[0:3], v[200:203], v[240:243], v[40:43]
	v_mfma_f32_16x16x32_bf16 v[92:95], v[204:207], v[134:137], v[0:3]
	v_mfma_f32_16x16x32_bf16 v[0:3], v[232:235], v[8:11], v[36:39]
	v_mfma_f32_16x16x32_bf16 v[72:75], v[236:239], v[12:15], v[0:3]
	v_mfma_f32_16x16x32_bf16 v[0:3], v[232:235], v[240:243], v[32:35]
	v_mfma_f32_16x16x32_bf16 v[76:79], v[236:239], v[134:137], v[0:3]
	s_setprio 0
	s_barrier
	ds_read_b128 v[24:27], v129 offset:49152
	ds_read_b128 v[28:31], v129 offset:50176
	ds_read_b128 v[44:47], v130 offset:49152
	ds_read_b128 v[200:203], v130 offset:50176
	ds_read_b128 v[204:207], v131 offset:49152
	ds_read_b128 v[232:235], v131 offset:50176
	ds_read_b128 v[236:239], v132 offset:49152
	ds_read_b128 v[130:133], v132 offset:50176
	s_cmp_eq_u32 s21, 15
	s_cbranch_scc1 .Lt3_d_skip
	s_add_i32 m0, s16, 0x18000
	s_nop 0
	buffer_load_dwordx4 v244, s[4:7], s24 offen lds
	s_add_i32 m0, s16, 0x1a000
	s_nop 0
	buffer_load_dwordx4 v244, s[4:7], s25 offen lds
	s_mov_b32 m0, s47
	s_nop 0
	buffer_load_dwordx4 v244, s[56:59], s24 offen lds
	s_mov_b32 m0, s67
	s_nop 0
	buffer_load_dwordx4 v244, s[56:59], s25 offen lds
.Lt3_d_skip:
	s_barrier
	s_waitcnt lgkmcnt(0)
	s_setprio 1
	s_waitcnt lgkmcnt(7)
	v_mfma_f32_16x16x32_bf16 v[0:3], v[24:27], v[184:187], v[208:211]
	s_waitcnt lgkmcnt(6)
	v_mfma_f32_16x16x32_bf16 v[48:51], v[28:31], v[188:191], v[0:3]
	v_mfma_f32_16x16x32_bf16 v[0:3], v[24:27], v[192:195], v[212:215]
	v_mfma_f32_16x16x32_bf16 v[52:55], v[28:31], v[196:199], v[0:3]
	s_waitcnt lgkmcnt(5)
	v_mfma_f32_16x16x32_bf16 v[0:3], v[44:47], v[184:187], v[216:219]
	s_waitcnt lgkmcnt(4)
	v_mfma_f32_16x16x32_bf16 v[32:35], v[200:203], v[188:191], v[0:3]
	v_mfma_f32_16x16x32_bf16 v[0:3], v[44:47], v[192:195], v[220:223]
	v_mfma_f32_16x16x32_bf16 v[36:39], v[200:203], v[196:199], v[0:3]
	s_waitcnt lgkmcnt(3)
	v_mfma_f32_16x16x32_bf16 v[0:3], v[204:207], v[184:187], v[224:227]
	s_waitcnt lgkmcnt(2)
	v_mfma_f32_16x16x32_bf16 v[16:19], v[232:235], v[188:191], v[0:3]
	v_mfma_f32_16x16x32_bf16 v[0:3], v[204:207], v[192:195], v[228:231]
	v_mfma_f32_16x16x32_bf16 v[20:23], v[232:235], v[196:199], v[0:3]
	s_waitcnt lgkmcnt(1)
	v_mfma_f32_16x16x32_bf16 v[0:3], v[236:239], v[184:187], v[144:147]
	v_mfma_f32_16x16x32_bf16 v[4:7], v[236:239], v[192:195], v[148:151]
	s_waitcnt lgkmcnt(0)
	v_mfma_f32_16x16x32_bf16 v[0:3], v[130:133], v[188:191], v[0:3]
	v_mfma_f32_16x16x32_bf16 v[4:7], v[130:133], v[196:199], v[4:7]
	s_setprio 0
	s_setprio 1
	v_mfma_f32_16x16x32_bf16 v[40:43], v[24:27], v[8:11], v[152:155]
	v_mfma_f32_16x16x32_bf16 v[24:27], v[24:27], v[240:243], v[156:159]
	v_mfma_f32_16x16x32_bf16 v[60:63], v[28:31], v[134:137], v[24:27]
	v_mfma_f32_16x16x32_bf16 v[24:27], v[44:47], v[8:11], v[160:163]
	v_mfma_f32_16x16x32_bf16 v[56:59], v[28:31], v[12:15], v[40:43]
	v_mfma_f32_16x16x32_bf16 v[40:43], v[200:203], v[12:15], v[24:27]
	v_mfma_f32_16x16x32_bf16 v[24:27], v[44:47], v[240:243], v[164:167]
	v_mfma_f32_16x16x32_bf16 v[44:47], v[200:203], v[134:137], v[24:27]
	v_mfma_f32_16x16x32_bf16 v[24:27], v[204:207], v[8:11], v[168:171]
	v_mfma_f32_16x16x32_bf16 v[8:11], v[236:239], v[8:11], v[176:179]
	v_mfma_f32_16x16x32_bf16 v[24:27], v[232:235], v[12:15], v[24:27]
	v_mfma_f32_16x16x32_bf16 v[28:31], v[204:207], v[240:243], v[172:175]
	v_mfma_f32_16x16x32_bf16 v[8:11], v[130:133], v[12:15], v[8:11]
	v_mfma_f32_16x16x32_bf16 v[12:15], v[236:239], v[240:243], v[180:183]
	v_mfma_f32_16x16x32_bf16 v[28:31], v[232:235], v[134:137], v[28:31]
	v_mfma_f32_16x16x32_bf16 v[12:15], v[130:133], v[134:137], v[12:15]
	s_setprio 0
	v_cmp_gt_u32_e32 vcc, s0, v128
	s_barrier
	s_and_saveexec_b64 s[4:5], vcc
	s_cbranch_execz .LBB0_268
	s_barrier
.LBB0_268:
	s_or_b64 exec, exec, s[4:5]
	s_cmp_eq_u32 s21, 15
	s_cbranch_scc1 .Lpf3_skip
	s_add_i32 s14, s21, 1
	s_lshl_b32 s14, s14, 19
	s_add_u32 s4, s1, s14
	s_addc_u32 s5, s20, 0
	s_and_b32 s5, s5, 0xffff
	s_mov_b32 m0, s78
	s_nop 0
	buffer_load_dwordx4 v244, s[4:7], s26 offen lds
	s_mov_b32 m0, s79
	s_nop 0
	buffer_load_dwordx4 v244, s[4:7], s27 offen lds

; #define WAIT_V(n) asm volatile("s_waitcnt vmcnt(" #n ")" ::: "memory")
; #define BAR __builtin_amdgcn_s_barrier()
; template <bool PEEL = false>
; __device__ __forceinline__ void gemm_tile(f32x4 (&acc)[2][2][4][2], const u16* __restrict__ A, int lda,
;                                           const u16* __restrict__ B, int K) {
;     ...
;   STAGE_B(SB(0, 0), 0, 0); STAGE_A(SA(0, 0), 0, 0);
;   STAGE_B(SB(0, 1), 1, 0); STAGE_A(SA(0, 1), 1, 0);
;   if (wr == 1) BAR;
;   WAIT_V(4); BAR;
;   STAGE_B(SB(1, 0), 0, 1); STAGE_A(SA(1, 0), 0, 1); STAGE_B(SB(1, 1), 1, 1);
; __device__ __forceinline__ void gemm_ffn_up(const u16* __restrict__ A, const u16* __restrict__ Wt, u16* __restrict__ hid) {
;     ...
;   for (int nt = 0; nt < 22; ++nt) {
;     f32x4 acc[2][2][4][2];
;     gemm_tile<true>(acc, A, 1024, Wt + (size_t)nt * 256 * 1024, 1024);
.LBB0_442:
	s_or_b64 exec, exec, s[2:3]
	s_cmp_eq_u32 s9, 21
	s_cbranch_scc1 .Lpf2_skip
	s_mov_b32 m0, s84
	s_nop 0
	buffer_load_dwordx4 v244, s[4:7], s14 offen lds
	s_mov_b32 m0, s85
	s_nop 0
	buffer_load_dwordx4 v244, s[4:7], s15 offen lds

.LBB0_446:
	ds_read_b128 v[144:147], v139
	ds_read_b128 v[148:151], v139 offset:1024
	ds_read_b128 v[152:155], v139 offset:2048
	ds_read_b128 v[156:159], v139 offset:3072
	s_mov_b32 m0, s87
	s_add_i32 s90, s89, 0xfffdff00
	ds_read_b128 v[160:163], v134
	ds_read_b128 v[164:167], v134 offset:1024
	ds_read_b128 v[168:171], v135
	ds_read_b128 v[172:175], v135 offset:1024
	ds_read_b128 v[176:179], v136
	ds_read_b128 v[180:183], v136 offset:1024
	ds_read_b128 v[184:187], v137
	ds_read_b128 v[188:191], v137 offset:1024
	buffer_load_dwordx4 v138, s[56:59], s90 offen lds
	s_add_i32 s90, s89, 0xffffff00
	s_mov_b32 m0, s86
	s_nop 0
	buffer_load_dwordx4 v138, s[56:59], s90 offen lds
	s_waitcnt lgkmcnt(8)
	s_barrier
	s_waitcnt lgkmcnt(0)
	s_setprio 1
	s_waitcnt lgkmcnt(7)
	v_mfma_f32_16x16x32_bf16 v[28:31], v[160:163], v[144:147], v[28:31]
	v_mfma_f32_16x16x32_bf16 v[24:27], v[160:163], v[152:155], v[24:27]
	s_waitcnt lgkmcnt(5)
	v_mfma_f32_16x16x32_bf16 v[20:23], v[168:171], v[144:147], v[20:23]
	v_mfma_f32_16x16x32_bf16 v[16:19], v[168:171], v[152:155], v[16:19]
	s_waitcnt lgkmcnt(3)
	v_mfma_f32_16x16x32_bf16 v[12:15], v[176:179], v[144:147], v[12:15]
	v_mfma_f32_16x16x32_bf16 v[8:11], v[176:179], v[152:155], v[8:11]
	s_waitcnt lgkmcnt(1)
	v_mfma_f32_16x16x32_bf16 v[4:7], v[184:187], v[144:147], v[4:7]
	v_mfma_f32_16x16x32_bf16 v[0:3], v[184:187], v[152:155], v[0:3]
	v_mfma_f32_16x16x32_bf16 v[28:31], v[164:167], v[148:151], v[28:31]
	v_mfma_f32_16x16x32_bf16 v[24:27], v[164:167], v[156:159], v[24:27]
	v_mfma_f32_16x16x32_bf16 v[20:23], v[172:175], v[148:151], v[20:23]
	v_mfma_f32_16x16x32_bf16 v[16:19], v[172:175], v[156:159], v[16:19]
	v_mfma_f32_16x16x32_bf16 v[12:15], v[180:183], v[148:151], v[12:15]
	v_mfma_f32_16x16x32_bf16 v[8:11], v[180:183], v[156:159], v[8:11]
	s_waitcnt lgkmcnt(0)
	v_mfma_f32_16x16x32_bf16 v[4:7], v[188:191], v[148:151], v[4:7]
	v_mfma_f32_16x16x32_bf16 v[0:3], v[188:191], v[156:159], v[0:3]
	s_setprio 0
	s_barrier
	s_mov_b32 m0, s65
	s_add_i32 s90, s89, 0xfff9ff80
	ds_read_b128 v[192:195], v140
	ds_read_b128 v[196:199], v140 offset:1024
	ds_read_b128 v[200:203], v140 offset:2048
	ds_read_b128 v[204:207], v140 offset:3072
	buffer_load_dwordx4 v138, s[4:7], s90 offen lds
	s_add_i32 s91, s89, 0xfffbff80
	s_mov_b32 m0, s66
	s_nop 0
	buffer_load_dwordx4 v138, s[4:7], s91 offen lds
	s_barrier
	s_waitcnt lgkmcnt(0)
	s_setprio 1
	s_waitcnt lgkmcnt(3)
	v_mfma_f32_16x16x32_bf16 v[60:63], v[160:163], v[192:195], v[60:63]
	s_waitcnt lgkmcnt(1)
	v_mfma_f32_16x16x32_bf16 v[56:59], v[160:163], v[200:203], v[56:59]
	v_mfma_f32_16x16x32_bf16 v[52:55], v[168:171], v[192:195], v[52:55]
	v_mfma_f32_16x16x32_bf16 v[48:51], v[168:171], v[200:203], v[48:51]
	v_mfma_f32_16x16x32_bf16 v[44:47], v[176:179], v[192:195], v[44:47]
	v_mfma_f32_16x16x32_bf16 v[40:43], v[176:179], v[200:203], v[40:43]
	v_mfma_f32_16x16x32_bf16 v[36:39], v[184:187], v[192:195], v[36:39]
	v_mfma_f32_16x16x32_bf16 v[32:35], v[184:187], v[200:203], v[32:35]
	v_mfma_f32_16x16x32_bf16 v[60:63], v[164:167], v[196:199], v[60:63]
	s_waitcnt lgkmcnt(0)
	v_mfma_f32_16x16x32_bf16 v[56:59], v[164:167], v[204:207], v[56:59]
	v_mfma_f32_16x16x32_bf16 v[52:55], v[172:175], v[196:199], v[52:55]
	v_mfma_f32_16x16x32_bf16 v[48:51], v[172:175], v[204:207], v[48:51]
	v_mfma_f32_16x16x32_bf16 v[44:47], v[180:183], v[196:199], v[44:47]
	v_mfma_f32_16x16x32_bf16 v[40:43], v[180:183], v[204:207], v[40:43]
	v_mfma_f32_16x16x32_bf16 v[36:39], v[188:191], v[196:199], v[36:39]
	v_mfma_f32_16x16x32_bf16 v[32:35], v[188:191], v[204:207], v[32:35]
	s_setprio 0
	s_mov_b32 m0, s64
	s_barrier
	ds_read_b128 v[160:163], v134 offset:16384
	ds_read_b128 v[164:167], v134 offset:17408
	ds_read_b128 v[168:171], v135 offset:16384
	ds_read_b128 v[172:175], v135 offset:17408
	ds_read_b128 v[176:179], v136 offset:16384
	ds_read_b128 v[180:183], v136 offset:17408
	ds_read_b128 v[184:187], v137 offset:16384
	ds_read_b128 v[188:191], v137 offset:17408
	buffer_load_dwordx4 v138, s[56:59], s90 offen lds
	s_mov_b32 m0, s67
	s_nop 0
	buffer_load_dwordx4 v138, s[56:59], s91 offen lds
	s_barrier
	s_waitcnt lgkmcnt(0)
	s_setprio 1
	s_waitcnt lgkmcnt(7)
	v_mfma_f32_16x16x32_bf16 v[92:95], v[160:163], v[144:147], v[92:95]
	v_mfma_f32_16x16x32_bf16 v[88:91], v[160:163], v[152:155], v[88:91]
	s_waitcnt lgkmcnt(5)
	v_mfma_f32_16x16x32_bf16 v[84:87], v[168:171], v[144:147], v[84:87]
	v_mfma_f32_16x16x32_bf16 v[80:83], v[168:171], v[152:155], v[80:83]
	s_waitcnt lgkmcnt(3)
	v_mfma_f32_16x16x32_bf16 v[76:79], v[176:179], v[144:147], v[76:79]
	v_mfma_f32_16x16x32_bf16 v[72:75], v[176:179], v[152:155], v[72:75]
	s_waitcnt lgkmcnt(1)
	v_mfma_f32_16x16x32_bf16 v[68:71], v[184:187], v[144:147], v[68:71]
	v_mfma_f32_16x16x32_bf16 v[64:67], v[184:187], v[152:155], v[64:67]
	v_mfma_f32_16x16x32_bf16 v[92:95], v[164:167], v[148:151], v[92:95]
	v_mfma_f32_16x16x32_bf16 v[88:91], v[164:167], v[156:159], v[88:91]
	v_mfma_f32_16x16x32_bf16 v[84:87], v[172:175], v[148:151], v[84:87]
	v_mfma_f32_16x16x32_bf16 v[80:83], v[172:175], v[156:159], v[80:83]
	v_mfma_f32_16x16x32_bf16 v[76:79], v[180:183], v[148:151], v[76:79]
	v_mfma_f32_16x16x32_bf16 v[72:75], v[180:183], v[156:159], v[72:75]
	s_waitcnt lgkmcnt(0)
	v_mfma_f32_16x16x32_bf16 v[68:71], v[188:191], v[148:151], v[68:71]
	v_mfma_f32_16x16x32_bf16 v[64:67], v[188:191], v[156:159], v[64:67]
	s_setprio 0
	s_barrier
	s_mov_b32 m0, s78
	s_add_i32 s90, s89, 0xfffdff80
	buffer_load_dwordx4 v138, s[4:7], s90 offen lds
	s_add_i32 s91, s89, 0xffffff80
	s_mov_b32 m0, s79
	s_nop 0
	buffer_load_dwordx4 v138, s[4:7], s91 offen lds
	s_waitcnt vmcnt(6)
	s_barrier
	s_setprio 1
	v_mfma_f32_16x16x32_bf16 v[124:127], v[160:163], v[192:195], v[124:127]
	v_mfma_f32_16x16x32_bf16 v[120:123], v[160:163], v[200:203], v[120:123]
	v_mfma_f32_16x16x32_bf16 v[116:119], v[168:171], v[192:195], v[116:119]
	v_mfma_f32_16x16x32_bf16 v[112:115], v[168:171], v[200:203], v[112:115]
	v_mfma_f32_16x16x32_bf16 v[108:111], v[176:179], v[192:195], v[108:111]
	v_mfma_f32_16x16x32_bf16 v[104:107], v[176:179], v[200:203], v[104:107]
	v_mfma_f32_16x16x32_bf16 v[100:103], v[184:187], v[192:195], v[100:103]
	v_mfma_f32_16x16x32_bf16 v[96:99], v[184:187], v[200:203], v[96:99]
	v_mfma_f32_16x16x32_bf16 v[124:127], v[164:167], v[196:199], v[124:127]
	v_mfma_f32_16x16x32_bf16 v[120:123], v[164:167], v[204:207], v[120:123]
	v_mfma_f32_16x16x32_bf16 v[116:119], v[172:175], v[196:199], v[116:119]
	v_mfma_f32_16x16x32_bf16 v[112:115], v[172:175], v[204:207], v[112:115]
	v_mfma_f32_16x16x32_bf16 v[108:111], v[180:183], v[196:199], v[108:111]
	v_mfma_f32_16x16x32_bf16 v[104:107], v[180:183], v[204:207], v[104:107]
	v_mfma_f32_16x16x32_bf16 v[100:103], v[188:191], v[196:199], v[100:103]
	v_mfma_f32_16x16x32_bf16 v[96:99], v[188:191], v[204:207], v[96:99]
	s_setprio 0
	s_barrier
	ds_read_b128 v[144:147], v141
	ds_read_b128 v[148:151], v141 offset:1024
	ds_read_b128 v[152:155], v141 offset:2048
	ds_read_b128 v[156:159], v141 offset:3072
	s_mov_b32 m0, s80
	ds_read_b128 v[160:163], v134 offset:32768
	ds_read_b128 v[164:167], v134 offset:33792
	ds_read_b128 v[168:171], v135 offset:32768
	ds_read_b128 v[172:175], v135 offset:33792
	ds_read_b128 v[176:179], v136 offset:32768
	ds_read_b128 v[180:183], v136 offset:33792
	ds_read_b128 v[184:187], v137 offset:32768
	ds_read_b128 v[188:191], v137 offset:33792
	buffer_load_dwordx4 v138, s[56:59], s90 offen lds
	s_mov_b32 m0, s81
	s_nop 0
	buffer_load_dwordx4 v138, s[56:59], s91 offen lds
	s_waitcnt lgkmcnt(8)
	s_barrier
	s_waitcnt lgkmcnt(0)
	s_setprio 1
	s_waitcnt lgkmcnt(7)
	v_mfma_f32_16x16x32_bf16 v[28:31], v[160:163], v[144:147], v[28:31]
	v_mfma_f32_16x16x32_bf16 v[24:27], v[160:163], v[152:155], v[24:27]
	s_waitcnt lgkmcnt(5)
	v_mfma_f32_16x16x32_bf16 v[20:23], v[168:171], v[144:147], v[20:23]
	v_mfma_f32_16x16x32_bf16 v[16:19], v[168:171], v[152:155], v[16:19]
	s_waitcnt lgkmcnt(3)
	v_mfma_f32_16x16x32_bf16 v[12:15], v[176:179], v[144:147], v[12:15]
	v_mfma_f32_16x16x32_bf16 v[8:11], v[176:179], v[152:155], v[8:11]
	s_waitcnt lgkmcnt(1)
	v_mfma_f32_16x16x32_bf16 v[4:7], v[184:187], v[144:147], v[4:7]
	v_mfma_f32_16x16x32_bf16 v[0:3], v[184:187], v[152:155], v[0:3]
	v_mfma_f32_16x16x32_bf16 v[28:31], v[164:167], v[148:151], v[28:31]
	v_mfma_f32_16x16x32_bf16 v[24:27], v[164:167], v[156:159], v[24:27]
	v_mfma_f32_16x16x32_bf16 v[20:23], v[172:175], v[148:151], v[20:23]
	v_mfma_f32_16x16x32_bf16 v[16:19], v[172:175], v[156:159], v[16:19]
	v_mfma_f32_16x16x32_bf16 v[12:15], v[180:183], v[148:151], v[12:15]
	v_mfma_f32_16x16x32_bf16 v[8:11], v[180:183], v[156:159], v[8:11]
	s_waitcnt lgkmcnt(0)
	v_mfma_f32_16x16x32_bf16 v[4:7], v[188:191], v[148:151], v[4:7]
	v_mfma_f32_16x16x32_bf16 v[0:3], v[188:191], v[156:159], v[0:3]
	s_setprio 0
	s_barrier
	s_mov_b32 m0, s2
	s_add_i32 s90, s89, 0xfffa0000
	ds_read_b128 v[192:195], v142
	ds_read_b128 v[196:199], v142 offset:1024
	ds_read_b128 v[200:203], v142 offset:2048
	ds_read_b128 v[204:207], v142 offset:3072
	buffer_load_dwordx4 v138, s[4:7], s90 offen lds
	s_add_i32 s91, s89, 0xfffc0000
	s_mov_b32 m0, s3
	s_nop 0
	buffer_load_dwordx4 v138, s[4:7], s91 offen lds
	s_barrier
	s_waitcnt lgkmcnt(0)
	s_setprio 1
	s_waitcnt lgkmcnt(3)
	v_mfma_f32_16x16x32_bf16 v[60:63], v[160:163], v[192:195], v[60:63]
	s_waitcnt lgkmcnt(1)
	v_mfma_f32_16x16x32_bf16 v[56:59], v[160:163], v[200:203], v[56:59]
	v_mfma_f32_16x16x32_bf16 v[52:55], v[168:171], v[192:195], v[52:55]
	v_mfma_f32_16x16x32_bf16 v[48:51], v[168:171], v[200:203], v[48:51]
	v_mfma_f32_16x16x32_bf16 v[44:47], v[176:179], v[192:195], v[44:47]
	v_mfma_f32_16x16x32_bf16 v[40:43], v[176:179], v[200:203], v[40:43]
	v_mfma_f32_16x16x32_bf16 v[36:39], v[184:187], v[192:195], v[36:39]
	v_mfma_f32_16x16x32_bf16 v[32:35], v[184:187], v[200:203], v[32:35]
	v_mfma_f32_16x16x32_bf16 v[60:63], v[164:167], v[196:199], v[60:63]
	s_waitcnt lgkmcnt(0)
	v_mfma_f32_16x16x32_bf16 v[56:59], v[164:167], v[204:207], v[56:59]
	v_mfma_f32_16x16x32_bf16 v[52:55], v[172:175], v[196:199], v[52:55]
	v_mfma_f32_16x16x32_bf16 v[48:51], v[172:175], v[204:207], v[48:51]
	v_mfma_f32_16x16x32_bf16 v[44:47], v[180:183], v[196:199], v[44:47]
	v_mfma_f32_16x16x32_bf16 v[40:43], v[180:183], v[204:207], v[40:43]
	v_mfma_f32_16x16x32_bf16 v[36:39], v[188:191], v[196:199], v[36:39]
	v_mfma_f32_16x16x32_bf16 v[32:35], v[188:191], v[204:207], v[32:35]
	s_setprio 0
	s_mov_b32 m0, s82
	s_barrier
	ds_read_b128 v[160:163], v134 offset:49152
	ds_read_b128 v[164:167], v134 offset:50176
	ds_read_b128 v[168:171], v135 offset:49152
	ds_read_b128 v[172:175], v135 offset:50176
	ds_read_b128 v[176:179], v136 offset:49152
	ds_read_b128 v[180:183], v136 offset:50176
	ds_read_b128 v[184:187], v137 offset:49152
	ds_read_b128 v[188:191], v137 offset:50176
	buffer_load_dwordx4 v138, s[56:59], s90 offen lds
	s_mov_b32 m0, s83
	s_nop 0
	buffer_load_dwordx4 v138, s[56:59], s91 offen lds
	s_barrier
; #define LDA(dst, b, h)                                                                             \
;   _Pragma("unroll") for (int m = 0; m < 4; ++m) _Pragma("unroll") for (int k = 0; k < 2; ++k)      \
;       dst[m][k] = *reinterpret_cast<const bf16x8*>(SA(b, h) + lds_byte(wr * 64 + m * 16 + fr, k * 32 + fq * 8))
; #define LDB(dst, b, h)                                                                             \
;   _Pragma("unroll") for (int n = 0; n < 2; ++n) _Pragma("unroll") for (int k = 0; k < 2; ++k)      \
;       dst[n][k] = *reinterpret_cast<const bf16x8*>(SB(b, h) + lds_byte(wc * 32 + n * 16 + fr, k * 32 + fq * 8))
; #define WAIT_V(n) asm volatile("s_waitcnt vmcnt(" #n ")" ::: "memory")
; #define WAIT_L(n) asm volatile("s_waitcnt lgkmcnt(" #n ")" ::: "memory")
; #define BAR __builtin_amdgcn_s_barrier()
; template <bool PEEL = false>
; __device__ __forceinline__ void gemm_tile(f32x4 (&acc)[2][2][4][2], const u16* __restrict__ A, int lda,
;                                           const u16* __restrict__ B, int K) {
;     ...
;   {
;     LDB(B0, 0, 0); LDA(At, 0, 0); STAGE_A(SA(1, 1), 1, nt - 1);
;     BAR; WAIT_L(0); MMA(0, 0, At, B0); BAR;
;     LDB(B1, 0, 1); BAR; WAIT_L(0); MMA(0, 1, At, B1); BAR;
;     LDA(At, 0, 1); WAIT_V(4); BAR; WAIT_L(0); MMA(1, 0, At, B0); MMA(1, 1, At, B1); BAR;
;   }
	s_waitcnt lgkmcnt(0)
	s_setprio 1
	s_waitcnt lgkmcnt(7)
	v_mfma_f32_16x16x32_bf16 v[92:95], v[160:163], v[144:147], v[92:95]
	v_mfma_f32_16x16x32_bf16 v[88:91], v[160:163], v[152:155], v[88:91]
	s_waitcnt lgkmcnt(5)
	v_mfma_f32_16x16x32_bf16 v[84:87], v[168:171], v[144:147], v[84:87]
	v_mfma_f32_16x16x32_bf16 v[80:83], v[168:171], v[152:155], v[80:83]
	s_waitcnt lgkmcnt(3)
	v_mfma_f32_16x16x32_bf16 v[76:79], v[176:179], v[144:147], v[76:79]
	v_mfma_f32_16x16x32_bf16 v[72:75], v[176:179], v[152:155], v[72:75]
	s_waitcnt lgkmcnt(1)
	v_mfma_f32_16x16x32_bf16 v[68:71], v[184:187], v[144:147], v[68:71]
	v_mfma_f32_16x16x32_bf16 v[64:67], v[184:187], v[152:155], v[64:67]
	v_mfma_f32_16x16x32_bf16 v[92:95], v[164:167], v[148:151], v[92:95]
	v_mfma_f32_16x16x32_bf16 v[88:91], v[164:167], v[156:159], v[88:91]
	v_mfma_f32_16x16x32_bf16 v[84:87], v[172:175], v[148:151], v[84:87]
	v_mfma_f32_16x16x32_bf16 v[80:83], v[172:175], v[156:159], v[80:83]
	v_mfma_f32_16x16x32_bf16 v[76:79], v[180:183], v[148:151], v[76:79]
	v_mfma_f32_16x16x32_bf16 v[72:75], v[180:183], v[156:159], v[72:75]
	s_waitcnt lgkmcnt(0)
	v_mfma_f32_16x16x32_bf16 v[68:71], v[188:191], v[148:151], v[68:71]
	v_mfma_f32_16x16x32_bf16 v[64:67], v[188:191], v[156:159], v[64:67]
	s_setprio 0
	s_barrier
	s_add_i32 s90, s89, 0xfffe0000
	s_mov_b32 m0, s84
	s_nop 0
	buffer_load_dwordx4 v138, s[4:7], s90 offen lds
	s_mov_b32 m0, s85
	s_nop 0
	buffer_load_dwordx4 v138, s[4:7], s89 offen lds
	s_waitcnt vmcnt(6)
	s_barrier
	s_setprio 1
	v_mfma_f32_16x16x32_bf16 v[124:127], v[160:163], v[192:195], v[124:127]
	v_mfma_f32_16x16x32_bf16 v[120:123], v[160:163], v[200:203], v[120:123]
	v_mfma_f32_16x16x32_bf16 v[116:119], v[168:171], v[192:195], v[116:119]
	v_mfma_f32_16x16x32_bf16 v[112:115], v[168:171], v[200:203], v[112:115]
	v_mfma_f32_16x16x32_bf16 v[108:111], v[176:179], v[192:195], v[108:111]
	v_mfma_f32_16x16x32_bf16 v[104:107], v[176:179], v[200:203], v[104:107]
	v_mfma_f32_16x16x32_bf16 v[100:103], v[184:187], v[192:195], v[100:103]
	v_mfma_f32_16x16x32_bf16 v[96:99], v[184:187], v[200:203], v[96:99]
	v_mfma_f32_16x16x32_bf16 v[124:127], v[164:167], v[196:199], v[124:127]
	v_mfma_f32_16x16x32_bf16 v[120:123], v[164:167], v[204:207], v[120:123]
	v_mfma_f32_16x16x32_bf16 v[116:119], v[172:175], v[196:199], v[116:119]
	v_mfma_f32_16x16x32_bf16 v[112:115], v[172:175], v[204:207], v[112:115]
	v_mfma_f32_16x16x32_bf16 v[108:111], v[180:183], v[196:199], v[108:111]
	v_mfma_f32_16x16x32_bf16 v[104:107], v[180:183], v[204:207], v[104:107]
	v_mfma_f32_16x16x32_bf16 v[100:103], v[188:191], v[196:199], v[100:103]
	v_mfma_f32_16x16x32_bf16 v[96:99], v[188:191], v[204:207], v[96:99]
	s_setprio 0
	s_add_i32 s88, s88, 2
	s_addk_i32 s89, 0x100
	s_cmp_lt_u32 s88, 12
	s_barrier
	s_cbranch_scc1 .LBB0_446
	v_mov_b32_e32 v244, v138
	s_mov_b32 m0, s87
	s_mov_b32 s2, 0x40780
	ds_read_b128 v[144:147], v139
	ds_read_b128 v[148:151], v139 offset:1024
	ds_read_b128 v[152:155], v139 offset:2048
	ds_read_b128 v[156:159], v139 offset:3072
	ds_read_b128 v[160:163], v134
	ds_read_b128 v[164:167], v134 offset:1024
	ds_read_b128 v[168:171], v135
	ds_read_b128 v[172:175], v135 offset:1024
	ds_read_b128 v[176:179], v136
	ds_read_b128 v[180:183], v136 offset:1024
	ds_read_b128 v[184:187], v137
	ds_read_b128 v[188:191], v137 offset:1024
	buffer_load_dwordx4 v138, s[56:59], s2 offen lds
	s_mov_b32 s2, 0x60780
	s_mov_b32 m0, s86
	s_nop 0
	buffer_load_dwordx4 v138, s[56:59], s2 offen lds
	s_barrier
	s_waitcnt lgkmcnt(0)
	s_setprio 1
	s_waitcnt lgkmcnt(7)
	v_mfma_f32_16x16x32_bf16 v[28:31], v[160:163], v[144:147], v[28:31]
	v_mfma_f32_16x16x32_bf16 v[24:27], v[160:163], v[152:155], v[24:27]
	s_waitcnt lgkmcnt(5)
	v_mfma_f32_16x16x32_bf16 v[20:23], v[168:171], v[144:147], v[20:23]
	v_mfma_f32_16x16x32_bf16 v[16:19], v[168:171], v[152:155], v[16:19]
	s_waitcnt lgkmcnt(3)
	v_mfma_f32_16x16x32_bf16 v[12:15], v[176:179], v[144:147], v[12:15]
	v_mfma_f32_16x16x32_bf16 v[8:11], v[176:179], v[152:155], v[8:11]
	s_waitcnt lgkmcnt(1)
	v_mfma_f32_16x16x32_bf16 v[4:7], v[184:187], v[144:147], v[4:7]
	v_mfma_f32_16x16x32_bf16 v[0:3], v[184:187], v[152:155], v[0:3]
	v_mfma_f32_16x16x32_bf16 v[28:31], v[164:167], v[148:151], v[28:31]
	v_mfma_f32_16x16x32_bf16 v[24:27], v[164:167], v[156:159], v[24:27]
	v_mfma_f32_16x16x32_bf16 v[20:23], v[172:175], v[148:151], v[20:23]
	v_mfma_f32_16x16x32_bf16 v[16:19], v[172:175], v[156:159], v[16:19]
	v_mfma_f32_16x16x32_bf16 v[12:15], v[180:183], v[148:151], v[12:15]
	v_mfma_f32_16x16x32_bf16 v[8:11], v[180:183], v[156:159], v[8:11]
	s_waitcnt lgkmcnt(0)
	v_mfma_f32_16x16x32_bf16 v[4:7], v[188:191], v[148:151], v[4:7]
	v_mfma_f32_16x16x32_bf16 v[0:3], v[188:191], v[156:159], v[0:3]
	s_setprio 0
	s_barrier
	ds_read_b128 v[192:195], v140
	ds_read_b128 v[196:199], v140 offset:1024
	ds_read_b128 v[200:203], v140 offset:2048
	ds_read_b128 v[204:207], v140 offset:3072
	s_barrier
	s_waitcnt lgkmcnt(0)
	s_setprio 1
	s_waitcnt lgkmcnt(3)
	v_mfma_f32_16x16x32_bf16 v[60:63], v[160:163], v[192:195], v[60:63]
	s_waitcnt lgkmcnt(1)
	v_mfma_f32_16x16x32_bf16 v[56:59], v[160:163], v[200:203], v[56:59]
	v_mfma_f32_16x16x32_bf16 v[52:55], v[168:171], v[192:195], v[52:55]
	v_mfma_f32_16x16x32_bf16 v[48:51], v[168:171], v[200:203], v[48:51]
	v_mfma_f32_16x16x32_bf16 v[44:47], v[176:179], v[192:195], v[44:47]
	v_mfma_f32_16x16x32_bf16 v[40:43], v[176:179], v[200:203], v[40:43]
	v_mfma_f32_16x16x32_bf16 v[36:39], v[184:187], v[192:195], v[36:39]
	v_mfma_f32_16x16x32_bf16 v[32:35], v[184:187], v[200:203], v[32:35]
	v_mfma_f32_16x16x32_bf16 v[60:63], v[164:167], v[196:199], v[60:63]
	s_waitcnt lgkmcnt(0)
	v_mfma_f32_16x16x32_bf16 v[56:59], v[164:167], v[204:207], v[56:59]
	v_mfma_f32_16x16x32_bf16 v[52:55], v[172:175], v[196:199], v[52:55]
	v_mfma_f32_16x16x32_bf16 v[48:51], v[172:175], v[204:207], v[48:51]
	v_mfma_f32_16x16x32_bf16 v[44:47], v[180:183], v[196:199], v[44:47]
	v_mfma_f32_16x16x32_bf16 v[40:43], v[180:183], v[204:207], v[40:43]
	v_mfma_f32_16x16x32_bf16 v[36:39], v[188:191], v[196:199], v[36:39]
	v_mfma_f32_16x16x32_bf16 v[32:35], v[188:191], v[204:207], v[32:35]
	s_setprio 0
	s_barrier
	ds_read_b128 v[160:163], v134 offset:16384
	ds_read_b128 v[164:167], v134 offset:17408
	ds_read_b128 v[168:171], v135 offset:16384
	ds_read_b128 v[172:175], v135 offset:17408
	ds_read_b128 v[176:179], v136 offset:16384
	ds_read_b128 v[180:183], v136 offset:17408
	ds_read_b128 v[184:187], v137 offset:16384
	ds_read_b128 v[188:191], v137 offset:17408
	s_cmp_eq_u32 s9, 21
	s_cbranch_scc1 .Lt2_a_last
	s_add_u32 s4, s4, 0x80000
	s_addc_u32 s5, s5, 0
	s_mov_b32 m0, s65
	s_nop 0
	buffer_load_dwordx4 v244, s[4:7], 0 offen lds
	s_mov_b32 m0, s66
	s_nop 0
	buffer_load_dwordx4 v244, s[4:7], s7 offen lds
	s_mov_b32 m0, s64
	s_nop 0
	buffer_load_dwordx4 v244, s[56:59], 0 offen lds
	s_mov_b32 m0, s67
	s_nop 0
	buffer_load_dwordx4 v244, s[56:59], s7 offen lds
	s_waitcnt vmcnt(8)
	s_branch .Lt2_a_join

; #define LDA(dst, b, h)                                                                             \
;   _Pragma("unroll") for (int m = 0; m < 4; ++m) _Pragma("unroll") for (int k = 0; k < 2; ++k)      \
;       dst[m][k] = *reinterpret_cast<const bf16x8*>(SA(b, h) + lds_byte(wr * 64 + m * 16 + fr, k * 32 + fq * 8))
; #define LDB(dst, b, h)                                                                             \
;   _Pragma("unroll") for (int n = 0; n < 2; ++n) _Pragma("unroll") for (int k = 0; k < 2; ++k)      \
;       dst[n][k] = *reinterpret_cast<const bf16x8*>(SB(b, h) + lds_byte(wc * 32 + n * 16 + fr, k * 32 + fq * 8))
; #define WAIT_V(n) asm volatile("s_waitcnt vmcnt(" #n ")" ::: "memory")
; #define WAIT_L(n) asm volatile("s_waitcnt lgkmcnt(" #n ")" ::: "memory")
; #define BAR __builtin_amdgcn_s_barrier()
; template <bool PEEL = false>
; __device__ __forceinline__ void gemm_tile(f32x4 (&acc)[2][2][4][2], const u16* __restrict__ A, int lda,
;                                           const u16* __restrict__ B, int K) {
;     ...
;     LDA(At, 0, 1); WAIT_V(4); BAR; WAIT_L(0); MMA(1, 0, At, B0); MMA(1, 1, At, B1); BAR;
;   }
;   {
;     LDB(B0, 1, 0); LDA(At, 1, 0); WAIT_V(2); BAR; WAIT_L(0); MMA(0, 0, At, B0); BAR;
.Lt2_a_join:
	s_barrier
	s_waitcnt lgkmcnt(0)
	s_setprio 1
	s_waitcnt lgkmcnt(7)
	v_mfma_f32_16x16x32_bf16 v[92:95], v[160:163], v[144:147], v[92:95]
	v_mfma_f32_16x16x32_bf16 v[88:91], v[160:163], v[152:155], v[88:91]
	s_waitcnt lgkmcnt(5)
	v_mfma_f32_16x16x32_bf16 v[84:87], v[168:171], v[144:147], v[84:87]
	v_mfma_f32_16x16x32_bf16 v[80:83], v[168:171], v[152:155], v[80:83]
	s_waitcnt lgkmcnt(3)
	v_mfma_f32_16x16x32_bf16 v[76:79], v[176:179], v[144:147], v[76:79]
	v_mfma_f32_16x16x32_bf16 v[72:75], v[176:179], v[152:155], v[72:75]
	s_waitcnt lgkmcnt(1)
	v_mfma_f32_16x16x32_bf16 v[68:71], v[184:187], v[144:147], v[68:71]
	v_mfma_f32_16x16x32_bf16 v[64:67], v[184:187], v[152:155], v[64:67]
	v_mfma_f32_16x16x32_bf16 v[208:211], v[164:167], v[148:151], v[92:95]
	v_mfma_f32_16x16x32_bf16 v[212:215], v[164:167], v[156:159], v[88:91]
	v_mfma_f32_16x16x32_bf16 v[216:219], v[172:175], v[148:151], v[84:87]
	v_mfma_f32_16x16x32_bf16 v[220:223], v[172:175], v[156:159], v[80:83]
	v_mfma_f32_16x16x32_bf16 v[224:227], v[180:183], v[148:151], v[76:79]
	v_mfma_f32_16x16x32_bf16 v[228:231], v[180:183], v[156:159], v[72:75]
	s_waitcnt lgkmcnt(0)
	v_mfma_f32_16x16x32_bf16 v[144:147], v[188:191], v[148:151], v[68:71]
	v_mfma_f32_16x16x32_bf16 v[148:151], v[188:191], v[156:159], v[64:67]
	s_setprio 0
	s_setprio 1
	v_mfma_f32_16x16x32_bf16 v[64:67], v[160:163], v[192:195], v[124:127]
	v_mfma_f32_16x16x32_bf16 v[152:155], v[164:167], v[196:199], v[64:67]
	v_mfma_f32_16x16x32_bf16 v[64:67], v[160:163], v[200:203], v[120:123]
	v_mfma_f32_16x16x32_bf16 v[156:159], v[164:167], v[204:207], v[64:67]
	v_mfma_f32_16x16x32_bf16 v[64:67], v[168:171], v[192:195], v[116:119]
	v_mfma_f32_16x16x32_bf16 v[160:163], v[172:175], v[196:199], v[64:67]
	v_mfma_f32_16x16x32_bf16 v[64:67], v[168:171], v[200:203], v[112:115]
	v_mfma_f32_16x16x32_bf16 v[164:167], v[172:175], v[204:207], v[64:67]
	v_mfma_f32_16x16x32_bf16 v[64:67], v[176:179], v[192:195], v[108:111]
	v_mfma_f32_16x16x32_bf16 v[168:171], v[180:183], v[196:199], v[64:67]
	v_mfma_f32_16x16x32_bf16 v[64:67], v[176:179], v[200:203], v[104:107]
	v_mfma_f32_16x16x32_bf16 v[172:175], v[180:183], v[204:207], v[64:67]
	v_mfma_f32_16x16x32_bf16 v[64:67], v[184:187], v[192:195], v[100:103]
	v_mfma_f32_16x16x32_bf16 v[176:179], v[188:191], v[196:199], v[64:67]
	v_mfma_f32_16x16x32_bf16 v[64:67], v[184:187], v[200:203], v[96:99]
	v_mfma_f32_16x16x32_bf16 v[180:183], v[188:191], v[204:207], v[64:67]
	s_setprio 0
	s_barrier
	ds_read_b128 v[184:187], v141
	ds_read_b128 v[188:191], v141 offset:1024
	ds_read_b128 v[192:195], v141 offset:2048
	ds_read_b128 v[138:141], v141 offset:3072
	ds_read_b128 v[72:75], v134 offset:32768
	ds_read_b128 v[76:79], v134 offset:33792
	ds_read_b128 v[88:91], v135 offset:32768
	ds_read_b128 v[92:95], v135 offset:33792
	ds_read_b128 v[196:199], v136 offset:32768
	ds_read_b128 v[200:203], v136 offset:33792
	ds_read_b128 v[204:207], v137 offset:32768
	ds_read_b128 v[232:235], v137 offset:33792
	s_cmp_eq_u32 s9, 21
	s_cbranch_scc1 .Lt2_b_last
	s_mov_b32 m0, s78
	s_nop 0
	buffer_load_dwordx4 v244, s[4:7], s10 offen lds
	s_mov_b32 m0, s79
	s_nop 0
	buffer_load_dwordx4 v244, s[4:7], s11 offen lds
	s_waitcnt vmcnt(8)
	s_branch .Lt2_b_join

; #define LDA(dst, b, h)                                                                             \
;   _Pragma("unroll") for (int m = 0; m < 4; ++m) _Pragma("unroll") for (int k = 0; k < 2; ++k)      \
;       dst[m][k] = *reinterpret_cast<const bf16x8*>(SA(b, h) + lds_byte(wr * 64 + m * 16 + fr, k * 32 + fq * 8))
; #define LDB(dst, b, h)                                                                             \
;   _Pragma("unroll") for (int n = 0; n < 2; ++n) _Pragma("unroll") for (int k = 0; k < 2; ++k)      \
;       dst[n][k] = *reinterpret_cast<const bf16x8*>(SB(b, h) + lds_byte(wc * 32 + n * 16 + fr, k * 32 + fq * 8))
; #define WAIT_V(n) asm volatile("s_waitcnt vmcnt(" #n ")" ::: "memory")
; #define WAIT_L(n) asm volatile("s_waitcnt lgkmcnt(" #n ")" ::: "memory")
; #define BAR __builtin_amdgcn_s_barrier()
; template <bool PEEL = false>
; __device__ __forceinline__ void gemm_tile(f32x4 (&acc)[2][2][4][2], const u16* __restrict__ A, int lda,
;                                           const u16* __restrict__ B, int K) {
;     ...
;     LDB(B0, 1, 0); LDA(At, 1, 0); WAIT_V(2); BAR; WAIT_L(0); MMA(0, 0, At, B0); BAR;
;     LDB(B1, 1, 1); WAIT_V(0); BAR; WAIT_L(0); MMA(0, 1, At, B1); BAR;
.Lt2_b_join:
	s_barrier
	s_waitcnt lgkmcnt(0)
	s_setprio 1
	s_waitcnt lgkmcnt(7)
	v_mfma_f32_16x16x32_bf16 v[28:31], v[72:75], v[184:187], v[28:31]
	v_mfma_f32_16x16x32_bf16 v[24:27], v[72:75], v[192:195], v[24:27]
	s_waitcnt lgkmcnt(5)
	v_mfma_f32_16x16x32_bf16 v[20:23], v[88:91], v[184:187], v[20:23]
	v_mfma_f32_16x16x32_bf16 v[16:19], v[88:91], v[192:195], v[16:19]
	s_waitcnt lgkmcnt(3)
	v_mfma_f32_16x16x32_bf16 v[12:15], v[196:199], v[184:187], v[12:15]
	v_mfma_f32_16x16x32_bf16 v[8:11], v[196:199], v[192:195], v[8:11]
	s_waitcnt lgkmcnt(1)
	v_mfma_f32_16x16x32_bf16 v[4:7], v[204:207], v[184:187], v[4:7]
	v_mfma_f32_16x16x32_bf16 v[0:3], v[204:207], v[192:195], v[0:3]
	v_mfma_f32_16x16x32_bf16 v[116:119], v[76:79], v[188:191], v[28:31]
	v_mfma_f32_16x16x32_bf16 v[112:115], v[76:79], v[138:141], v[24:27]
	v_mfma_f32_16x16x32_bf16 v[100:103], v[92:95], v[188:191], v[20:23]
	v_mfma_f32_16x16x32_bf16 v[96:99], v[92:95], v[138:141], v[16:19]
	v_mfma_f32_16x16x32_bf16 v[84:87], v[200:203], v[188:191], v[12:15]
	v_mfma_f32_16x16x32_bf16 v[80:83], v[200:203], v[138:141], v[8:11]
	s_waitcnt lgkmcnt(0)
	v_mfma_f32_16x16x32_bf16 v[68:71], v[232:235], v[188:191], v[4:7]
	v_mfma_f32_16x16x32_bf16 v[64:67], v[232:235], v[138:141], v[0:3]
	s_setprio 0
	s_barrier
	ds_read_b128 v[4:7], v142
	ds_read_b128 v[12:15], v142 offset:1024
	ds_read_b128 v[236:239], v142 offset:2048
	ds_read_b128 v[240:243], v142 offset:3072
	s_cmp_eq_u32 s9, 21
	s_cbranch_scc1 .Lt2_c_last
	s_mov_b32 m0, s80
	s_nop 0
	buffer_load_dwordx4 v244, s[56:59], s10 offen lds
	s_mov_b32 m0, s81
	s_nop 0
	buffer_load_dwordx4 v244, s[56:59], s11 offen lds
	s_waitcnt vmcnt(8)
	s_branch .Lt2_c_join

; #define LDA(dst, b, h)                                                                             \
;   _Pragma("unroll") for (int m = 0; m < 4; ++m) _Pragma("unroll") for (int k = 0; k < 2; ++k)      \
;       dst[m][k] = *reinterpret_cast<const bf16x8*>(SA(b, h) + lds_byte(wr * 64 + m * 16 + fr, k * 32 + fq * 8))
; #define LDB(dst, b, h)                                                                             \
;   _Pragma("unroll") for (int n = 0; n < 2; ++n) _Pragma("unroll") for (int k = 0; k < 2; ++k)      \
;       dst[n][k] = *reinterpret_cast<const bf16x8*>(SB(b, h) + lds_byte(wc * 32 + n * 16 + fr, k * 32 + fq * 8))
; #define WAIT_V(n) asm volatile("s_waitcnt vmcnt(" #n ")" ::: "memory")
; #define WAIT_L(n) asm volatile("s_waitcnt lgkmcnt(" #n ")" ::: "memory")
; #define BAR __builtin_amdgcn_s_barrier()
; template <bool PEEL = false>
; __device__ __forceinline__ void gemm_tile(f32x4 (&acc)[2][2][4][2], const u16* __restrict__ A, int lda,
;                                           const u16* __restrict__ B, int K) {
;     ...
;   STAGE_B(SB(1, 0), 0, 1); STAGE_A(SA(1, 0), 0, 1); STAGE_B(SB(1, 1), 1, 1);
;     ...
;   {
;     LDB(B0, 1, 0); LDA(At, 1, 0); WAIT_V(2); BAR; WAIT_L(0); MMA(0, 0, At, B0); BAR;
;     LDB(B1, 1, 1); WAIT_V(0); BAR; WAIT_L(0); MMA(0, 1, At, B1); BAR;
;     LDA(At, 1, 1); BAR; WAIT_L(0); MMA(1, 0, At, B0); MMA(1, 1, At, B1); BAR;
;   }
;   if (wr == 0) BAR;
.Lt2_c_join:
	s_barrier
	s_waitcnt lgkmcnt(0)
	s_setprio 1
	s_waitcnt lgkmcnt(3)
	v_mfma_f32_16x16x32_bf16 v[0:3], v[72:75], v[4:7], v[60:63]
	s_waitcnt lgkmcnt(2)
	v_mfma_f32_16x16x32_bf16 v[124:127], v[76:79], v[12:15], v[0:3]
	s_waitcnt lgkmcnt(1)
	v_mfma_f32_16x16x32_bf16 v[0:3], v[72:75], v[236:239], v[56:59]
	s_waitcnt lgkmcnt(0)
	v_mfma_f32_16x16x32_bf16 v[120:123], v[76:79], v[240:243], v[0:3]
	v_mfma_f32_16x16x32_bf16 v[0:3], v[88:91], v[4:7], v[52:55]
	v_mfma_f32_16x16x32_bf16 v[108:111], v[92:95], v[12:15], v[0:3]
	v_mfma_f32_16x16x32_bf16 v[0:3], v[88:91], v[236:239], v[48:51]
	v_mfma_f32_16x16x32_bf16 v[104:107], v[92:95], v[240:243], v[0:3]
	v_mfma_f32_16x16x32_bf16 v[0:3], v[196:199], v[4:7], v[44:47]
	v_mfma_f32_16x16x32_bf16 v[92:95], v[200:203], v[12:15], v[0:3]
	v_mfma_f32_16x16x32_bf16 v[0:3], v[196:199], v[236:239], v[40:43]
	v_mfma_f32_16x16x32_bf16 v[88:91], v[200:203], v[240:243], v[0:3]
	v_mfma_f32_16x16x32_bf16 v[0:3], v[204:207], v[4:7], v[36:39]
	v_mfma_f32_16x16x32_bf16 v[76:79], v[232:235], v[12:15], v[0:3]
	v_mfma_f32_16x16x32_bf16 v[0:3], v[204:207], v[236:239], v[32:35]
	v_mfma_f32_16x16x32_bf16 v[72:75], v[232:235], v[240:243], v[0:3]
	s_setprio 0
	s_barrier
	ds_read_b128 v[24:27], v134 offset:49152
	ds_read_b128 v[28:31], v134 offset:50176
	ds_read_b128 v[36:39], v135 offset:49152
	ds_read_b128 v[196:199], v135 offset:50176
	ds_read_b128 v[200:203], v136 offset:49152
	ds_read_b128 v[204:207], v136 offset:50176
	ds_read_b128 v[232:235], v137 offset:49152
	ds_read_b128 v[134:137], v137 offset:50176
	s_cmp_eq_u32 s9, 21
	s_cbranch_scc1 .Lt2_d_skip
	s_add_i32 m0, s64, 0x18000
	s_nop 0
	buffer_load_dwordx4 v244, s[4:7], s12 offen lds
	s_add_i32 m0, s64, 0x1a000
	s_nop 0
	buffer_load_dwordx4 v244, s[4:7], s13 offen lds
	s_mov_b32 m0, s82
	s_nop 0
	buffer_load_dwordx4 v244, s[56:59], s12 offen lds
	s_mov_b32 m0, s83
	s_nop 0
	buffer_load_dwordx4 v244, s[56:59], s13 offen lds
.Lt2_d_skip:
	s_barrier
	s_waitcnt lgkmcnt(0)
	s_setprio 1
	s_waitcnt lgkmcnt(7)
	v_mfma_f32_16x16x32_bf16 v[0:3], v[24:27], v[184:187], v[208:211]
	s_waitcnt lgkmcnt(6)
	v_mfma_f32_16x16x32_bf16 v[52:55], v[28:31], v[188:191], v[0:3]
	v_mfma_f32_16x16x32_bf16 v[0:3], v[24:27], v[192:195], v[212:215]
	v_mfma_f32_16x16x32_bf16 v[48:51], v[28:31], v[138:141], v[0:3]
	s_waitcnt lgkmcnt(5)
	v_mfma_f32_16x16x32_bf16 v[0:3], v[36:39], v[184:187], v[216:219]
	s_waitcnt lgkmcnt(4)
	v_mfma_f32_16x16x32_bf16 v[40:43], v[196:199], v[188:191], v[0:3]
	v_mfma_f32_16x16x32_bf16 v[0:3], v[36:39], v[192:195], v[220:223]
	v_mfma_f32_16x16x32_bf16 v[32:35], v[196:199], v[138:141], v[0:3]
	s_waitcnt lgkmcnt(3)
	v_mfma_f32_16x16x32_bf16 v[0:3], v[200:203], v[184:187], v[224:227]
	s_waitcnt lgkmcnt(2)
	v_mfma_f32_16x16x32_bf16 v[20:23], v[204:207], v[188:191], v[0:3]
	v_mfma_f32_16x16x32_bf16 v[0:3], v[200:203], v[192:195], v[228:231]
	v_mfma_f32_16x16x32_bf16 v[16:19], v[204:207], v[138:141], v[0:3]
	s_waitcnt lgkmcnt(1)
	v_mfma_f32_16x16x32_bf16 v[0:3], v[232:235], v[184:187], v[144:147]
	s_waitcnt lgkmcnt(0)
	v_mfma_f32_16x16x32_bf16 v[8:11], v[134:137], v[188:191], v[0:3]
	v_mfma_f32_16x16x32_bf16 v[0:3], v[232:235], v[192:195], v[148:151]
	v_mfma_f32_16x16x32_bf16 v[0:3], v[134:137], v[138:141], v[0:3]
	s_setprio 0
	s_setprio 1
	v_mfma_f32_16x16x32_bf16 v[44:47], v[24:27], v[4:7], v[152:155]
	v_mfma_f32_16x16x32_bf16 v[24:27], v[24:27], v[236:239], v[156:159]
	v_mfma_f32_16x16x32_bf16 v[56:59], v[28:31], v[240:243], v[24:27]
	v_mfma_f32_16x16x32_bf16 v[24:27], v[36:39], v[4:7], v[160:163]
	v_mfma_f32_16x16x32_bf16 v[60:63], v[28:31], v[12:15], v[44:47]
	v_mfma_f32_16x16x32_bf16 v[44:47], v[196:199], v[12:15], v[24:27]
	v_mfma_f32_16x16x32_bf16 v[24:27], v[36:39], v[236:239], v[164:167]
	v_mfma_f32_16x16x32_bf16 v[36:39], v[196:199], v[240:243], v[24:27]
	v_mfma_f32_16x16x32_bf16 v[24:27], v[200:203], v[4:7], v[168:171]
	v_mfma_f32_16x16x32_bf16 v[4:7], v[232:235], v[4:7], v[176:179]
	v_mfma_f32_16x16x32_bf16 v[28:31], v[204:207], v[12:15], v[24:27]
	v_mfma_f32_16x16x32_bf16 v[24:27], v[200:203], v[236:239], v[172:175]
	v_mfma_f32_16x16x32_bf16 v[12:15], v[134:137], v[12:15], v[4:7]
	v_mfma_f32_16x16x32_bf16 v[4:7], v[232:235], v[236:239], v[180:183]
	v_mfma_f32_16x16x32_bf16 v[24:27], v[204:207], v[240:243], v[24:27]
	v_mfma_f32_16x16x32_bf16 v[4:7], v[134:137], v[240:243], v[4:7]
	s_setprio 0
	v_cmp_gt_u32_e32 vcc, s0, v133
	s_barrier
	s_and_saveexec_b64 s[2:3], vcc
	s_cbranch_execz .LBB0_442
	s_barrier
	s_branch .LBB0_442
